# phase 1 hand-written: four rows in flight per wave, DPP wave reductions
# speedup vs baseline: 1.0095x; 1.0095x over previous
.LBB0_118:
	s_or_b64 exec, exec, s[2:3]
	s_barrier
	s_lshl_b32 s4, s92, 3
	v_writelane_b32 v248, s4, 9
	s_mov_b32 s5, 0
	v_mbcnt_lo_u32_b32 v193, -1, 0
	v_writelane_b32 v248, s5, 10
	s_load_dwordx4 s[8:11], s[0:1], 0x0
	s_load_dwordx2 s[12:13], s[0:1], 0x68
	s_load_dwordx2 s[14:15], s[0:1], 0xe8
	s_load_dwordx2 s[16:17], s[0:1], 0xf0
	v_readfirstlane_b32 s24, v192
	v_and_b32_e32 v246, 0x3f, v192
	v_lshlrev_b32_e32 v247, 0x3, v246
	v_lshlrev_b32_e32 v246, 0x4, v246
	s_lshr_b32 s24, s24, 6
	s_lshl_b32 s24, s24, 8
	s_add_u32 s24, s24, s96
	s_mov_b32 s39, 0x3a800000
	s_waitcnt lgkmcnt(0)
	s_add_u32 s18, s16, 0x2380000
	s_addc_u32 s19, s17, 0
	s_add_u32 s20, s16, 0x2740000
	s_addc_u32 s21, s17, 0
	s_add_u32 s22, s16, 0x26a0000
	s_addc_u32 s23, s17, 0
	s_add_u32 s14, s14, 0x4397020
	s_addc_u32 s15, s15, 0
	s_lshl_b32 s38, s24, 12
	s_add_u32 s8, s8, s38
	s_addc_u32 s9, s9, 0
	s_add_u32 s10, s10, s38
	s_addc_u32 s11, s11, 0
	s_lshl_b32 s38, s24, 11
	s_add_u32 s14, s14, s38
	s_addc_u32 s15, s15, 0
	s_lshl_b32 s38, s24, 5
	s_add_u32 s22, s22, s38
	s_addc_u32 s23, s23, 0
	s_load_dwordx8 s[52:59], s[12:13], 0x2000
	global_load_dwordx4 v[128:131], v246, s[8:9]
	global_load_dwordx4 v[132:135], v246, s[8:9] offset:1024
	global_load_dwordx4 v[136:139], v246, s[8:9] offset:2048
	global_load_dwordx4 v[140:143], v246, s[8:9] offset:3072
	s_add_u32 s34, s18, 0x0
	s_addc_u32 s35, s19, 0
	s_add_u32 s36, s34, 0x1000
	s_addc_u32 s37, s35, 0
	global_load_dwordx4 v[194:197], v246, s[34:35]
	global_load_dwordx4 v[198:201], v246, s[34:35] offset:1024
	global_load_dwordx4 v[202:205], v246, s[34:35] offset:2048
	global_load_dwordx4 v[206:209], v246, s[34:35] offset:3072
	global_load_dwordx4 v[210:213], v246, s[36:37]
	global_load_dwordx4 v[214:217], v246, s[36:37] offset:1024
	global_load_dwordx4 v[218:221], v246, s[36:37] offset:2048
	global_load_dwordx4 v[222:225], v246, s[36:37] offset:3072
	s_add_u32 s26, s8, 0x800000
	s_addc_u32 s27, s9, 0
	global_load_dwordx4 v[144:147], v246, s[26:27]
	global_load_dwordx4 v[148:151], v246, s[26:27] offset:1024
	global_load_dwordx4 v[152:155], v246, s[26:27] offset:2048
	global_load_dwordx4 v[156:159], v246, s[26:27] offset:3072
	global_load_dwordx4 v[0:3], v246, s[20:21]
	global_load_dwordx4 v[4:7], v246, s[20:21] offset:1024
	global_load_dwordx4 v[8:11], v246, s[20:21] offset:2048
	global_load_dwordx4 v[12:15], v246, s[20:21] offset:3072
	v_add_u32_e32 v239, 0x1000, v246
	global_load_dwordx4 v[16:19], v239, s[20:21]
	global_load_dwordx4 v[20:23], v239, s[20:21] offset:1024
	global_load_dwordx4 v[24:27], v239, s[20:21] offset:2048
	global_load_dwordx4 v[28:31], v239, s[20:21] offset:3072
	v_add_u32_e32 v238, 0x2000, v246
	global_load_dwordx4 v[32:35], v238, s[20:21]
	global_load_dwordx4 v[36:39], v238, s[20:21] offset:1024
	global_load_dwordx4 v[40:43], v238, s[20:21] offset:2048
	global_load_dwordx4 v[44:47], v238, s[20:21] offset:3072
	v_add_u32_e32 v239, 0x3000, v246
	global_load_dwordx4 v[48:51], v239, s[20:21]
	global_load_dwordx4 v[52:55], v239, s[20:21] offset:1024
	global_load_dwordx4 v[56:59], v239, s[20:21] offset:2048
	global_load_dwordx4 v[60:63], v239, s[20:21] offset:3072
	v_add_u32_e32 v238, 0x4000, v246
	global_load_dwordx4 v[64:67], v238, s[20:21]
	global_load_dwordx4 v[68:71], v238, s[20:21] offset:1024
	global_load_dwordx4 v[72:75], v238, s[20:21] offset:2048
	global_load_dwordx4 v[76:79], v238, s[20:21] offset:3072
	v_add_u32_e32 v239, 0x5000, v246
	global_load_dwordx4 v[80:83], v239, s[20:21]
	global_load_dwordx4 v[84:87], v239, s[20:21] offset:1024
	global_load_dwordx4 v[88:91], v239, s[20:21] offset:2048
	global_load_dwordx4 v[92:95], v239, s[20:21] offset:3072
	v_add_u32_e32 v238, 0x6000, v246
	global_load_dwordx4 v[96:99], v238, s[20:21]
	global_load_dwordx4 v[100:103], v238, s[20:21] offset:1024
	global_load_dwordx4 v[104:107], v238, s[20:21] offset:2048
	global_load_dwordx4 v[108:111], v238, s[20:21] offset:3072
	v_add_u32_e32 v239, 0x7000, v246
	global_load_dwordx4 v[112:115], v239, s[20:21]
	global_load_dwordx4 v[116:119], v239, s[20:21] offset:1024
	global_load_dwordx4 v[120:123], v239, s[20:21] offset:2048
	global_load_dwordx4 v[124:127], v239, s[20:21] offset:3072
	s_add_u32 s26, s8, 0x1000000
	s_addc_u32 s27, s9, 0
	global_load_dwordx4 v[160:163], v246, s[26:27]
	global_load_dwordx4 v[164:167], v246, s[26:27] offset:1024
	global_load_dwordx4 v[168:171], v246, s[26:27] offset:2048
	global_load_dwordx4 v[172:175], v246, s[26:27] offset:3072
	s_add_u32 s26, s8, 0x1800000
	s_addc_u32 s27, s9, 0
	global_load_dwordx4 v[176:179], v246, s[26:27]
	global_load_dwordx4 v[180:183], v246, s[26:27] offset:1024
	global_load_dwordx4 v[184:187], v246, s[26:27] offset:2048
	global_load_dwordx4 v[188:191], v246, s[26:27] offset:3072
	s_waitcnt lgkmcnt(0)
	s_waitcnt vmcnt(8)
	v_add_f32_e32 v210, 1.0, v210
	v_add_f32_e32 v211, 1.0, v211
	v_add_f32_e32 v212, 1.0, v212
	v_add_f32_e32 v213, 1.0, v213
	v_add_f32_e32 v214, 1.0, v214
	v_add_f32_e32 v215, 1.0, v215
	v_add_f32_e32 v216, 1.0, v216
	v_add_f32_e32 v217, 1.0, v217
	v_add_f32_e32 v218, 1.0, v218
	v_add_f32_e32 v219, 1.0, v219
	v_add_f32_e32 v220, 1.0, v220
	v_add_f32_e32 v221, 1.0, v221
	v_add_f32_e32 v222, 1.0, v222
	v_add_f32_e32 v223, 1.0, v223
	v_add_f32_e32 v224, 1.0, v224
	v_add_f32_e32 v225, 1.0, v225
	v_add_f32_e32 v234, v128, v129
	v_mul_f32_e32 v235, v128, v128
	v_add_f32_e32 v238, v130, v131
	v_mul_f32_e32 v239, v129, v129
	v_fmac_f32_e32 v235, v130, v130
	v_fmac_f32_e32 v239, v131, v131
	v_fmac_f32_e32 v235, v132, v132
	v_fmac_f32_e32 v239, v133, v133
	v_add_f32_e32 v234, v234, v132
	v_add_f32_e32 v238, v238, v133
	v_fmac_f32_e32 v235, v134, v134
	v_fmac_f32_e32 v239, v135, v135
	v_add_f32_e32 v234, v234, v134
	v_add_f32_e32 v238, v238, v135
	v_fmac_f32_e32 v235, v136, v136
	v_fmac_f32_e32 v239, v137, v137
	v_add_f32_e32 v234, v234, v136
	v_add_f32_e32 v238, v238, v137
	v_fmac_f32_e32 v235, v138, v138
	v_fmac_f32_e32 v239, v139, v139
	v_add_f32_e32 v234, v234, v138
	v_add_f32_e32 v238, v238, v139
	v_fmac_f32_e32 v235, v140, v140
	v_fmac_f32_e32 v239, v141, v141
	v_add_f32_e32 v234, v234, v140
	v_add_f32_e32 v238, v238, v141
	v_fmac_f32_e32 v235, v142, v142
	v_fmac_f32_e32 v239, v143, v143
	v_add_f32_e32 v234, v234, v142
	v_add_f32_e32 v238, v238, v143
	v_add_f32_e32 v234, v234, v238
	v_add_f32_e32 v235, v235, v239
	s_nop 1
	v_add_f32_dpp v234, v234, v234 quad_perm:[1,0,3,2] row_mask:0xf bank_mask:0xf
	v_add_f32_dpp v235, v235, v235 quad_perm:[1,0,3,2] row_mask:0xf bank_mask:0xf
	s_nop 1
	v_add_f32_dpp v234, v234, v234 quad_perm:[2,3,0,1] row_mask:0xf bank_mask:0xf
	v_add_f32_dpp v235, v235, v235 quad_perm:[2,3,0,1] row_mask:0xf bank_mask:0xf
	s_nop 1
	v_add_f32_dpp v234, v234, v234 row_half_mirror row_mask:0xf bank_mask:0xf
	v_add_f32_dpp v235, v235, v235 row_half_mirror row_mask:0xf bank_mask:0xf
	s_nop 1
	v_add_f32_dpp v234, v234, v234 row_mirror row_mask:0xf bank_mask:0xf
	v_add_f32_dpp v235, v235, v235 row_mirror row_mask:0xf bank_mask:0xf
	s_nop 1
	v_add_f32_dpp v234, v234, v234 row_bcast:15 row_mask:0xa bank_mask:0xf
	v_add_f32_dpp v235, v235, v235 row_bcast:15 row_mask:0xa bank_mask:0xf
	s_nop 1
	v_add_f32_dpp v234, v234, v234 row_bcast:31 row_mask:0xc bank_mask:0xf
	v_add_f32_dpp v235, v235, v235 row_bcast:31 row_mask:0xc bank_mask:0xf
	s_nop 1
	v_readlane_b32 s40, v234, 63
	v_readlane_b32 s41, v235, 63
	s_nop 3
	v_mov_b32_e32 v238, s40
	v_mov_b32_e32 v239, s41
	v_mul_f32_e32 v236, s39, v238
	v_mul_f32_e32 v239, s39, v239
	v_fma_f32 v239, -v236, v236, v239
	v_max_f32_e32 v239, 0x0, v239
	v_add_f32_e32 v239, 0x3727c5ac, v239
	v_rsq_f32_e32 v237, v239
	v_sub_f32_e32 v128, v128, v236
	v_sub_f32_e32 v129, v129, v236
	v_sub_f32_e32 v130, v130, v236
	v_sub_f32_e32 v131, v131, v236
	v_sub_f32_e32 v132, v132, v236
	v_sub_f32_e32 v133, v133, v236
	v_sub_f32_e32 v134, v134, v236
	v_sub_f32_e32 v135, v135, v236
	v_sub_f32_e32 v136, v136, v236
	v_sub_f32_e32 v137, v137, v236
	v_sub_f32_e32 v138, v138, v236
	v_sub_f32_e32 v139, v139, v236
	v_sub_f32_e32 v140, v140, v236
	v_sub_f32_e32 v141, v141, v236
	v_sub_f32_e32 v142, v142, v236
	v_sub_f32_e32 v143, v143, v236
	v_mul_f32_e32 v128, v128, v237
	v_mul_f32_e32 v129, v129, v237
	v_mul_f32_e32 v130, v130, v237
	v_mul_f32_e32 v131, v131, v237
	v_mul_f32_e32 v132, v132, v237
	v_mul_f32_e32 v133, v133, v237
	v_mul_f32_e32 v134, v134, v237
	v_mul_f32_e32 v135, v135, v237
	v_mul_f32_e32 v136, v136, v237
	v_mul_f32_e32 v137, v137, v237
	v_mul_f32_e32 v138, v138, v237
	v_mul_f32_e32 v139, v139, v237
	v_mul_f32_e32 v140, v140, v237
	v_mul_f32_e32 v141, v141, v237
	v_mul_f32_e32 v142, v142, v237
	v_mul_f32_e32 v143, v143, v237
	v_fma_f32 v128, v128, v210, v194
	v_fma_f32 v129, v129, v211, v195
	v_fma_f32 v130, v130, v212, v196
	v_fma_f32 v131, v131, v213, v197
	v_fma_f32 v132, v132, v214, v198
	v_fma_f32 v133, v133, v215, v199
	v_fma_f32 v134, v134, v216, v200
	v_fma_f32 v135, v135, v217, v201
	v_fma_f32 v136, v136, v218, v202
	v_fma_f32 v137, v137, v219, v203
	v_fma_f32 v138, v138, v220, v204
	v_fma_f32 v139, v139, v221, v205
	v_fma_f32 v140, v140, v222, v206
	v_fma_f32 v141, v141, v223, v207
	v_fma_f32 v142, v142, v224, v208
	v_fma_f32 v143, v143, v225, v209
	s_add_u32 s28, s14, 0x0
	s_addc_u32 s29, s15, 0
	s_add_u32 s30, s22, 0x0
	s_addc_u32 s31, s23, 0
	v_cvt_pk_bf16_f32 v238, v128, v129
	v_cvt_pk_bf16_f32 v239, v130, v131
	global_store_dwordx2 v247, v[238:239], s[28:29]
	v_cvt_pk_bf16_f32 v240, v132, v133
	v_cvt_pk_bf16_f32 v241, v134, v135
	global_store_dwordx2 v247, v[240:241], s[28:29] offset:512
	s_nop 0
	v_cvt_pk_bf16_f32 v238, v136, v137
	v_cvt_pk_bf16_f32 v239, v138, v139
	global_store_dwordx2 v247, v[238:239], s[28:29] offset:1024
	v_cvt_pk_bf16_f32 v240, v140, v141
	v_cvt_pk_bf16_f32 v241, v142, v143
	global_store_dwordx2 v247, v[240:241], s[28:29] offset:1536
	v_mul_f32_e32 v226, v128, v0
	v_mul_f32_e32 v227, v128, v16
	v_mul_f32_e32 v228, v128, v32
	v_mul_f32_e32 v229, v128, v48
	v_mul_f32_e32 v230, v128, v64
	v_mul_f32_e32 v231, v128, v80
	v_mul_f32_e32 v232, v128, v96
	v_mul_f32_e32 v233, v128, v112
	v_fmac_f32_e32 v226, v129, v1
	v_fmac_f32_e32 v227, v129, v17
	v_fmac_f32_e32 v228, v129, v33
	v_fmac_f32_e32 v229, v129, v49
	v_fmac_f32_e32 v230, v129, v65
	v_fmac_f32_e32 v231, v129, v81
	v_fmac_f32_e32 v232, v129, v97
	v_fmac_f32_e32 v233, v129, v113
	v_fmac_f32_e32 v226, v130, v2
	v_fmac_f32_e32 v227, v130, v18
	v_fmac_f32_e32 v228, v130, v34
	v_fmac_f32_e32 v229, v130, v50
	v_fmac_f32_e32 v230, v130, v66
	v_fmac_f32_e32 v231, v130, v82
	v_fmac_f32_e32 v232, v130, v98
	v_fmac_f32_e32 v233, v130, v114
	v_fmac_f32_e32 v226, v131, v3
	v_fmac_f32_e32 v227, v131, v19
	v_fmac_f32_e32 v228, v131, v35
	v_fmac_f32_e32 v229, v131, v51
	v_fmac_f32_e32 v230, v131, v67
	v_fmac_f32_e32 v231, v131, v83
	v_fmac_f32_e32 v232, v131, v99
	v_fmac_f32_e32 v233, v131, v115
	v_fmac_f32_e32 v226, v132, v4
	v_fmac_f32_e32 v227, v132, v20
	v_fmac_f32_e32 v228, v132, v36
	v_fmac_f32_e32 v229, v132, v52
	v_fmac_f32_e32 v230, v132, v68
	v_fmac_f32_e32 v231, v132, v84
	v_fmac_f32_e32 v232, v132, v100
	v_fmac_f32_e32 v233, v132, v116
	v_fmac_f32_e32 v226, v133, v5
	v_fmac_f32_e32 v227, v133, v21
	v_fmac_f32_e32 v228, v133, v37
	v_fmac_f32_e32 v229, v133, v53
	v_fmac_f32_e32 v230, v133, v69
	v_fmac_f32_e32 v231, v133, v85
	v_fmac_f32_e32 v232, v133, v101
	v_fmac_f32_e32 v233, v133, v117
	v_fmac_f32_e32 v226, v134, v6
	v_fmac_f32_e32 v227, v134, v22
	v_fmac_f32_e32 v228, v134, v38
	v_fmac_f32_e32 v229, v134, v54
	v_fmac_f32_e32 v230, v134, v70
	v_fmac_f32_e32 v231, v134, v86
	v_fmac_f32_e32 v232, v134, v102
	v_fmac_f32_e32 v233, v134, v118
	v_fmac_f32_e32 v226, v135, v7
	v_fmac_f32_e32 v227, v135, v23
	v_fmac_f32_e32 v228, v135, v39
	v_fmac_f32_e32 v229, v135, v55
	v_fmac_f32_e32 v230, v135, v71
	v_fmac_f32_e32 v231, v135, v87
	v_fmac_f32_e32 v232, v135, v103
	v_fmac_f32_e32 v233, v135, v119
	v_fmac_f32_e32 v226, v136, v8
	v_fmac_f32_e32 v227, v136, v24
	v_fmac_f32_e32 v228, v136, v40
	v_fmac_f32_e32 v229, v136, v56
	v_fmac_f32_e32 v230, v136, v72
	v_fmac_f32_e32 v231, v136, v88
	v_fmac_f32_e32 v232, v136, v104
	v_fmac_f32_e32 v233, v136, v120
	v_fmac_f32_e32 v226, v137, v9
	v_fmac_f32_e32 v227, v137, v25
	v_fmac_f32_e32 v228, v137, v41
	v_fmac_f32_e32 v229, v137, v57
	v_fmac_f32_e32 v230, v137, v73
	v_fmac_f32_e32 v231, v137, v89
	v_fmac_f32_e32 v232, v137, v105
	v_fmac_f32_e32 v233, v137, v121
	v_fmac_f32_e32 v226, v138, v10
	v_fmac_f32_e32 v227, v138, v26
	v_fmac_f32_e32 v228, v138, v42
	v_fmac_f32_e32 v229, v138, v58
	v_fmac_f32_e32 v230, v138, v74
	v_fmac_f32_e32 v231, v138, v90
	v_fmac_f32_e32 v232, v138, v106
	v_fmac_f32_e32 v233, v138, v122
	v_fmac_f32_e32 v226, v139, v11
	v_fmac_f32_e32 v227, v139, v27
	v_fmac_f32_e32 v228, v139, v43
	v_fmac_f32_e32 v229, v139, v59
	v_fmac_f32_e32 v230, v139, v75
	v_fmac_f32_e32 v231, v139, v91
	v_fmac_f32_e32 v232, v139, v107
	v_fmac_f32_e32 v233, v139, v123
	v_fmac_f32_e32 v226, v140, v12
	v_fmac_f32_e32 v227, v140, v28
	v_fmac_f32_e32 v228, v140, v44
	v_fmac_f32_e32 v229, v140, v60
	v_fmac_f32_e32 v230, v140, v76
	v_fmac_f32_e32 v231, v140, v92
	v_fmac_f32_e32 v232, v140, v108
	v_fmac_f32_e32 v233, v140, v124
	v_fmac_f32_e32 v226, v141, v13
	v_fmac_f32_e32 v227, v141, v29
	v_fmac_f32_e32 v228, v141, v45
	v_fmac_f32_e32 v229, v141, v61
	v_fmac_f32_e32 v230, v141, v77
	v_fmac_f32_e32 v231, v141, v93
	v_fmac_f32_e32 v232, v141, v109
	v_fmac_f32_e32 v233, v141, v125
	v_fmac_f32_e32 v226, v142, v14
	v_fmac_f32_e32 v227, v142, v30
	v_fmac_f32_e32 v228, v142, v46
	v_fmac_f32_e32 v229, v142, v62
	v_fmac_f32_e32 v230, v142, v78
	v_fmac_f32_e32 v231, v142, v94
	v_fmac_f32_e32 v232, v142, v110
	v_fmac_f32_e32 v233, v142, v126
	v_fmac_f32_e32 v226, v143, v15
	v_fmac_f32_e32 v227, v143, v31
	v_fmac_f32_e32 v228, v143, v47
	v_fmac_f32_e32 v229, v143, v63
	v_fmac_f32_e32 v230, v143, v79
	v_fmac_f32_e32 v231, v143, v95
	v_fmac_f32_e32 v232, v143, v111
	v_fmac_f32_e32 v233, v143, v127
	v_add_f32_dpp v226, v226, v226 quad_perm:[1,0,3,2] row_mask:0xf bank_mask:0xf
	v_add_f32_dpp v227, v227, v227 quad_perm:[1,0,3,2] row_mask:0xf bank_mask:0xf
	v_add_f32_dpp v228, v228, v228 quad_perm:[1,0,3,2] row_mask:0xf bank_mask:0xf
	v_add_f32_dpp v229, v229, v229 quad_perm:[1,0,3,2] row_mask:0xf bank_mask:0xf
	v_add_f32_dpp v230, v230, v230 quad_perm:[1,0,3,2] row_mask:0xf bank_mask:0xf
	v_add_f32_dpp v231, v231, v231 quad_perm:[1,0,3,2] row_mask:0xf bank_mask:0xf
	v_add_f32_dpp v232, v232, v232 quad_perm:[1,0,3,2] row_mask:0xf bank_mask:0xf
	v_add_f32_dpp v233, v233, v233 quad_perm:[1,0,3,2] row_mask:0xf bank_mask:0xf
	v_add_f32_dpp v226, v226, v226 quad_perm:[2,3,0,1] row_mask:0xf bank_mask:0xf
	v_add_f32_dpp v227, v227, v227 quad_perm:[2,3,0,1] row_mask:0xf bank_mask:0xf
	v_add_f32_dpp v228, v228, v228 quad_perm:[2,3,0,1] row_mask:0xf bank_mask:0xf
	v_add_f32_dpp v229, v229, v229 quad_perm:[2,3,0,1] row_mask:0xf bank_mask:0xf
	v_add_f32_dpp v230, v230, v230 quad_perm:[2,3,0,1] row_mask:0xf bank_mask:0xf
	v_add_f32_dpp v231, v231, v231 quad_perm:[2,3,0,1] row_mask:0xf bank_mask:0xf
	v_add_f32_dpp v232, v232, v232 quad_perm:[2,3,0,1] row_mask:0xf bank_mask:0xf
	v_add_f32_dpp v233, v233, v233 quad_perm:[2,3,0,1] row_mask:0xf bank_mask:0xf
	v_add_f32_dpp v226, v226, v226 row_half_mirror row_mask:0xf bank_mask:0xf
	v_add_f32_dpp v227, v227, v227 row_half_mirror row_mask:0xf bank_mask:0xf
	v_add_f32_dpp v228, v228, v228 row_half_mirror row_mask:0xf bank_mask:0xf
	v_add_f32_dpp v229, v229, v229 row_half_mirror row_mask:0xf bank_mask:0xf
	v_add_f32_dpp v230, v230, v230 row_half_mirror row_mask:0xf bank_mask:0xf
	v_add_f32_dpp v231, v231, v231 row_half_mirror row_mask:0xf bank_mask:0xf
	v_add_f32_dpp v232, v232, v232 row_half_mirror row_mask:0xf bank_mask:0xf
	v_add_f32_dpp v233, v233, v233 row_half_mirror row_mask:0xf bank_mask:0xf
	v_add_f32_dpp v226, v226, v226 row_mirror row_mask:0xf bank_mask:0xf
	v_add_f32_dpp v227, v227, v227 row_mirror row_mask:0xf bank_mask:0xf
	v_add_f32_dpp v228, v228, v228 row_mirror row_mask:0xf bank_mask:0xf
	v_add_f32_dpp v229, v229, v229 row_mirror row_mask:0xf bank_mask:0xf
	v_add_f32_dpp v230, v230, v230 row_mirror row_mask:0xf bank_mask:0xf
	v_add_f32_dpp v231, v231, v231 row_mirror row_mask:0xf bank_mask:0xf
	v_add_f32_dpp v232, v232, v232 row_mirror row_mask:0xf bank_mask:0xf
	v_add_f32_dpp v233, v233, v233 row_mirror row_mask:0xf bank_mask:0xf
	v_add_f32_dpp v226, v226, v226 row_bcast:15 row_mask:0xa bank_mask:0xf
	v_add_f32_dpp v227, v227, v227 row_bcast:15 row_mask:0xa bank_mask:0xf
	v_add_f32_dpp v228, v228, v228 row_bcast:15 row_mask:0xa bank_mask:0xf
	v_add_f32_dpp v229, v229, v229 row_bcast:15 row_mask:0xa bank_mask:0xf
	v_add_f32_dpp v230, v230, v230 row_bcast:15 row_mask:0xa bank_mask:0xf
	v_add_f32_dpp v231, v231, v231 row_bcast:15 row_mask:0xa bank_mask:0xf
	v_add_f32_dpp v232, v232, v232 row_bcast:15 row_mask:0xa bank_mask:0xf
	v_add_f32_dpp v233, v233, v233 row_bcast:15 row_mask:0xa bank_mask:0xf
	v_add_f32_dpp v226, v226, v226 row_bcast:31 row_mask:0xc bank_mask:0xf
	v_add_f32_dpp v227, v227, v227 row_bcast:31 row_mask:0xc bank_mask:0xf
	v_add_f32_dpp v228, v228, v228 row_bcast:31 row_mask:0xc bank_mask:0xf
	v_add_f32_dpp v229, v229, v229 row_bcast:31 row_mask:0xc bank_mask:0xf
	v_add_f32_dpp v230, v230, v230 row_bcast:31 row_mask:0xc bank_mask:0xf
	v_add_f32_dpp v231, v231, v231 row_bcast:31 row_mask:0xc bank_mask:0xf
	v_add_f32_dpp v232, v232, v232 row_bcast:31 row_mask:0xc bank_mask:0xf
	v_add_f32_dpp v233, v233, v233 row_bcast:31 row_mask:0xc bank_mask:0xf
	v_readlane_b32 s44, v226, 63
	v_readlane_b32 s45, v227, 63
	v_readlane_b32 s46, v228, 63
	v_readlane_b32 s47, v229, 63
	v_readlane_b32 s48, v230, 63
	v_readlane_b32 s49, v231, 63
	v_readlane_b32 s50, v232, 63
	v_readlane_b32 s51, v233, 63
	s_nop 3
	v_mov_b32_e32 v250, s44
	v_mov_b32_e32 v251, s45
	v_mov_b32_e32 v252, s46
	v_mov_b32_e32 v253, s47
	v_add_f32_e32 v250, s52, v250
	v_add_f32_e32 v251, s53, v251
	v_add_f32_e32 v252, s54, v252
	v_add_f32_e32 v253, s55, v253
	s_mov_b64 exec, 1
	global_store_dwordx4 v246, v[250:253], s[30:31]
	s_nop 1
	v_mov_b32_e32 v250, s48
	v_mov_b32_e32 v251, s49
	v_mov_b32_e32 v252, s50
	v_mov_b32_e32 v253, s51
	v_add_f32_e32 v250, s56, v250
	v_add_f32_e32 v251, s57, v251
	v_add_f32_e32 v252, s58, v252
	v_add_f32_e32 v253, s59, v253
	global_store_dwordx4 v246, v[250:253], s[30:31] offset:16
	s_mov_b64 exec, -1
	s_add_u32 s26, s8, 0x2000000
	s_addc_u32 s27, s9, 0
	global_load_dwordx4 v[128:131], v246, s[26:27]
	global_load_dwordx4 v[132:135], v246, s[26:27] offset:1024
	global_load_dwordx4 v[136:139], v246, s[26:27] offset:2048
	global_load_dwordx4 v[140:143], v246, s[26:27] offset:3072
	s_waitcnt vmcnt(18)
	v_add_f32_e32 v234, v144, v145
	v_mul_f32_e32 v235, v144, v144
	v_add_f32_e32 v238, v146, v147
	v_mul_f32_e32 v239, v145, v145
	v_fmac_f32_e32 v235, v146, v146
	v_fmac_f32_e32 v239, v147, v147
	v_fmac_f32_e32 v235, v148, v148
	v_fmac_f32_e32 v239, v149, v149
	v_add_f32_e32 v234, v234, v148
	v_add_f32_e32 v238, v238, v149
	v_fmac_f32_e32 v235, v150, v150
	v_fmac_f32_e32 v239, v151, v151
	v_add_f32_e32 v234, v234, v150
	v_add_f32_e32 v238, v238, v151
	v_fmac_f32_e32 v235, v152, v152
	v_fmac_f32_e32 v239, v153, v153
	v_add_f32_e32 v234, v234, v152
	v_add_f32_e32 v238, v238, v153
	v_fmac_f32_e32 v235, v154, v154
	v_fmac_f32_e32 v239, v155, v155
	v_add_f32_e32 v234, v234, v154
	v_add_f32_e32 v238, v238, v155
	v_fmac_f32_e32 v235, v156, v156
	v_fmac_f32_e32 v239, v157, v157
	v_add_f32_e32 v234, v234, v156
	v_add_f32_e32 v238, v238, v157
	v_fmac_f32_e32 v235, v158, v158
	v_fmac_f32_e32 v239, v159, v159
	v_add_f32_e32 v234, v234, v158
	v_add_f32_e32 v238, v238, v159
	v_add_f32_e32 v234, v234, v238
	v_add_f32_e32 v235, v235, v239
	s_nop 1
	v_add_f32_dpp v234, v234, v234 quad_perm:[1,0,3,2] row_mask:0xf bank_mask:0xf
	v_add_f32_dpp v235, v235, v235 quad_perm:[1,0,3,2] row_mask:0xf bank_mask:0xf
	s_nop 1
	v_add_f32_dpp v234, v234, v234 quad_perm:[2,3,0,1] row_mask:0xf bank_mask:0xf
	v_add_f32_dpp v235, v235, v235 quad_perm:[2,3,0,1] row_mask:0xf bank_mask:0xf
	s_nop 1
	v_add_f32_dpp v234, v234, v234 row_half_mirror row_mask:0xf bank_mask:0xf
	v_add_f32_dpp v235, v235, v235 row_half_mirror row_mask:0xf bank_mask:0xf
	s_nop 1
	v_add_f32_dpp v234, v234, v234 row_mirror row_mask:0xf bank_mask:0xf
	v_add_f32_dpp v235, v235, v235 row_mirror row_mask:0xf bank_mask:0xf
	s_nop 1
	v_add_f32_dpp v234, v234, v234 row_bcast:15 row_mask:0xa bank_mask:0xf
	v_add_f32_dpp v235, v235, v235 row_bcast:15 row_mask:0xa bank_mask:0xf
	s_nop 1
	v_add_f32_dpp v234, v234, v234 row_bcast:31 row_mask:0xc bank_mask:0xf
	v_add_f32_dpp v235, v235, v235 row_bcast:31 row_mask:0xc bank_mask:0xf
	s_nop 1
	v_readlane_b32 s40, v234, 63
	v_readlane_b32 s41, v235, 63
	s_nop 3
	v_mov_b32_e32 v238, s40
	v_mov_b32_e32 v239, s41
	v_mul_f32_e32 v236, s39, v238
	v_mul_f32_e32 v239, s39, v239
	v_fma_f32 v239, -v236, v236, v239
	v_max_f32_e32 v239, 0x0, v239
	v_add_f32_e32 v239, 0x3727c5ac, v239
	v_rsq_f32_e32 v237, v239
	v_sub_f32_e32 v144, v144, v236
	v_sub_f32_e32 v145, v145, v236
	v_sub_f32_e32 v146, v146, v236
	v_sub_f32_e32 v147, v147, v236
	v_sub_f32_e32 v148, v148, v236
	v_sub_f32_e32 v149, v149, v236
	v_sub_f32_e32 v150, v150, v236
	v_sub_f32_e32 v151, v151, v236
	v_sub_f32_e32 v152, v152, v236
	v_sub_f32_e32 v153, v153, v236
	v_sub_f32_e32 v154, v154, v236
	v_sub_f32_e32 v155, v155, v236
	v_sub_f32_e32 v156, v156, v236
	v_sub_f32_e32 v157, v157, v236
	v_sub_f32_e32 v158, v158, v236
	v_sub_f32_e32 v159, v159, v236
	v_mul_f32_e32 v144, v144, v237
	v_mul_f32_e32 v145, v145, v237
	v_mul_f32_e32 v146, v146, v237
	v_mul_f32_e32 v147, v147, v237
	v_mul_f32_e32 v148, v148, v237
	v_mul_f32_e32 v149, v149, v237
	v_mul_f32_e32 v150, v150, v237
	v_mul_f32_e32 v151, v151, v237
	v_mul_f32_e32 v152, v152, v237
	v_mul_f32_e32 v153, v153, v237
	v_mul_f32_e32 v154, v154, v237
	v_mul_f32_e32 v155, v155, v237
	v_mul_f32_e32 v156, v156, v237
	v_mul_f32_e32 v157, v157, v237
	v_mul_f32_e32 v158, v158, v237
	v_mul_f32_e32 v159, v159, v237
	v_fma_f32 v144, v144, v210, v194
	v_fma_f32 v145, v145, v211, v195
	v_fma_f32 v146, v146, v212, v196
	v_fma_f32 v147, v147, v213, v197
	v_fma_f32 v148, v148, v214, v198
	v_fma_f32 v149, v149, v215, v199
	v_fma_f32 v150, v150, v216, v200
	v_fma_f32 v151, v151, v217, v201
	v_fma_f32 v152, v152, v218, v202
	v_fma_f32 v153, v153, v219, v203
	v_fma_f32 v154, v154, v220, v204
	v_fma_f32 v155, v155, v221, v205
	v_fma_f32 v156, v156, v222, v206
	v_fma_f32 v157, v157, v223, v207
	v_fma_f32 v158, v158, v224, v208
	v_fma_f32 v159, v159, v225, v209
	s_add_u32 s28, s14, 0x400000
	s_addc_u32 s29, s15, 0
	s_add_u32 s30, s22, 0x10000
	s_addc_u32 s31, s23, 0
	v_cvt_pk_bf16_f32 v238, v144, v145
	v_cvt_pk_bf16_f32 v239, v146, v147
	global_store_dwordx2 v247, v[238:239], s[28:29]
	v_cvt_pk_bf16_f32 v240, v148, v149
	v_cvt_pk_bf16_f32 v241, v150, v151
	global_store_dwordx2 v247, v[240:241], s[28:29] offset:512
	s_nop 0
	v_cvt_pk_bf16_f32 v238, v152, v153
	v_cvt_pk_bf16_f32 v239, v154, v155
	global_store_dwordx2 v247, v[238:239], s[28:29] offset:1024
	v_cvt_pk_bf16_f32 v240, v156, v157
	v_cvt_pk_bf16_f32 v241, v158, v159
	global_store_dwordx2 v247, v[240:241], s[28:29] offset:1536
	v_mul_f32_e32 v226, v144, v0
	v_mul_f32_e32 v227, v144, v16
	v_mul_f32_e32 v228, v144, v32
	v_mul_f32_e32 v229, v144, v48
	v_mul_f32_e32 v230, v144, v64
	v_mul_f32_e32 v231, v144, v80
	v_mul_f32_e32 v232, v144, v96
	v_mul_f32_e32 v233, v144, v112
	v_fmac_f32_e32 v226, v145, v1
	v_fmac_f32_e32 v227, v145, v17
	v_fmac_f32_e32 v228, v145, v33
	v_fmac_f32_e32 v229, v145, v49
	v_fmac_f32_e32 v230, v145, v65
	v_fmac_f32_e32 v231, v145, v81
	v_fmac_f32_e32 v232, v145, v97
	v_fmac_f32_e32 v233, v145, v113
	v_fmac_f32_e32 v226, v146, v2
	v_fmac_f32_e32 v227, v146, v18
	v_fmac_f32_e32 v228, v146, v34
	v_fmac_f32_e32 v229, v146, v50
	v_fmac_f32_e32 v230, v146, v66
	v_fmac_f32_e32 v231, v146, v82
	v_fmac_f32_e32 v232, v146, v98
	v_fmac_f32_e32 v233, v146, v114
	v_fmac_f32_e32 v226, v147, v3
	v_fmac_f32_e32 v227, v147, v19
	v_fmac_f32_e32 v228, v147, v35
	v_fmac_f32_e32 v229, v147, v51
	v_fmac_f32_e32 v230, v147, v67
	v_fmac_f32_e32 v231, v147, v83
	v_fmac_f32_e32 v232, v147, v99
	v_fmac_f32_e32 v233, v147, v115
	v_fmac_f32_e32 v226, v148, v4
	v_fmac_f32_e32 v227, v148, v20
	v_fmac_f32_e32 v228, v148, v36
	v_fmac_f32_e32 v229, v148, v52
	v_fmac_f32_e32 v230, v148, v68
	v_fmac_f32_e32 v231, v148, v84
	v_fmac_f32_e32 v232, v148, v100
	v_fmac_f32_e32 v233, v148, v116
	v_fmac_f32_e32 v226, v149, v5
	v_fmac_f32_e32 v227, v149, v21
	v_fmac_f32_e32 v228, v149, v37
	v_fmac_f32_e32 v229, v149, v53
	v_fmac_f32_e32 v230, v149, v69
	v_fmac_f32_e32 v231, v149, v85
	v_fmac_f32_e32 v232, v149, v101
	v_fmac_f32_e32 v233, v149, v117
	v_fmac_f32_e32 v226, v150, v6
	v_fmac_f32_e32 v227, v150, v22
	v_fmac_f32_e32 v228, v150, v38
	v_fmac_f32_e32 v229, v150, v54
	v_fmac_f32_e32 v230, v150, v70
	v_fmac_f32_e32 v231, v150, v86
	v_fmac_f32_e32 v232, v150, v102
	v_fmac_f32_e32 v233, v150, v118
	v_fmac_f32_e32 v226, v151, v7
	v_fmac_f32_e32 v227, v151, v23
	v_fmac_f32_e32 v228, v151, v39
	v_fmac_f32_e32 v229, v151, v55
	v_fmac_f32_e32 v230, v151, v71
	v_fmac_f32_e32 v231, v151, v87
	v_fmac_f32_e32 v232, v151, v103
	v_fmac_f32_e32 v233, v151, v119
	v_fmac_f32_e32 v226, v152, v8
	v_fmac_f32_e32 v227, v152, v24
	v_fmac_f32_e32 v228, v152, v40
	v_fmac_f32_e32 v229, v152, v56
	v_fmac_f32_e32 v230, v152, v72
	v_fmac_f32_e32 v231, v152, v88
	v_fmac_f32_e32 v232, v152, v104
	v_fmac_f32_e32 v233, v152, v120
	v_fmac_f32_e32 v226, v153, v9
	v_fmac_f32_e32 v227, v153, v25
	v_fmac_f32_e32 v228, v153, v41
	v_fmac_f32_e32 v229, v153, v57
	v_fmac_f32_e32 v230, v153, v73
	v_fmac_f32_e32 v231, v153, v89
	v_fmac_f32_e32 v232, v153, v105
	v_fmac_f32_e32 v233, v153, v121
	v_fmac_f32_e32 v226, v154, v10
	v_fmac_f32_e32 v227, v154, v26
	v_fmac_f32_e32 v228, v154, v42
	v_fmac_f32_e32 v229, v154, v58
	v_fmac_f32_e32 v230, v154, v74
	v_fmac_f32_e32 v231, v154, v90
	v_fmac_f32_e32 v232, v154, v106
	v_fmac_f32_e32 v233, v154, v122
	v_fmac_f32_e32 v226, v155, v11
	v_fmac_f32_e32 v227, v155, v27
	v_fmac_f32_e32 v228, v155, v43
	v_fmac_f32_e32 v229, v155, v59
	v_fmac_f32_e32 v230, v155, v75
	v_fmac_f32_e32 v231, v155, v91
	v_fmac_f32_e32 v232, v155, v107
	v_fmac_f32_e32 v233, v155, v123
	v_fmac_f32_e32 v226, v156, v12
	v_fmac_f32_e32 v227, v156, v28
	v_fmac_f32_e32 v228, v156, v44
	v_fmac_f32_e32 v229, v156, v60
	v_fmac_f32_e32 v230, v156, v76
	v_fmac_f32_e32 v231, v156, v92
	v_fmac_f32_e32 v232, v156, v108
	v_fmac_f32_e32 v233, v156, v124
	v_fmac_f32_e32 v226, v157, v13
	v_fmac_f32_e32 v227, v157, v29
	v_fmac_f32_e32 v228, v157, v45
	v_fmac_f32_e32 v229, v157, v61
	v_fmac_f32_e32 v230, v157, v77
	v_fmac_f32_e32 v231, v157, v93
	v_fmac_f32_e32 v232, v157, v109
	v_fmac_f32_e32 v233, v157, v125
	v_fmac_f32_e32 v226, v158, v14
	v_fmac_f32_e32 v227, v158, v30
	v_fmac_f32_e32 v228, v158, v46
	v_fmac_f32_e32 v229, v158, v62
	v_fmac_f32_e32 v230, v158, v78
	v_fmac_f32_e32 v231, v158, v94
	v_fmac_f32_e32 v232, v158, v110
	v_fmac_f32_e32 v233, v158, v126
	v_fmac_f32_e32 v226, v159, v15
	v_fmac_f32_e32 v227, v159, v31
	v_fmac_f32_e32 v228, v159, v47
	v_fmac_f32_e32 v229, v159, v63
	v_fmac_f32_e32 v230, v159, v79
	v_fmac_f32_e32 v231, v159, v95
	v_fmac_f32_e32 v232, v159, v111
	v_fmac_f32_e32 v233, v159, v127
	v_add_f32_dpp v226, v226, v226 quad_perm:[1,0,3,2] row_mask:0xf bank_mask:0xf
	v_add_f32_dpp v227, v227, v227 quad_perm:[1,0,3,2] row_mask:0xf bank_mask:0xf
	v_add_f32_dpp v228, v228, v228 quad_perm:[1,0,3,2] row_mask:0xf bank_mask:0xf
	v_add_f32_dpp v229, v229, v229 quad_perm:[1,0,3,2] row_mask:0xf bank_mask:0xf
	v_add_f32_dpp v230, v230, v230 quad_perm:[1,0,3,2] row_mask:0xf bank_mask:0xf
	v_add_f32_dpp v231, v231, v231 quad_perm:[1,0,3,2] row_mask:0xf bank_mask:0xf
	v_add_f32_dpp v232, v232, v232 quad_perm:[1,0,3,2] row_mask:0xf bank_mask:0xf
	v_add_f32_dpp v233, v233, v233 quad_perm:[1,0,3,2] row_mask:0xf bank_mask:0xf
	v_add_f32_dpp v226, v226, v226 quad_perm:[2,3,0,1] row_mask:0xf bank_mask:0xf
	v_add_f32_dpp v227, v227, v227 quad_perm:[2,3,0,1] row_mask:0xf bank_mask:0xf
	v_add_f32_dpp v228, v228, v228 quad_perm:[2,3,0,1] row_mask:0xf bank_mask:0xf
	v_add_f32_dpp v229, v229, v229 quad_perm:[2,3,0,1] row_mask:0xf bank_mask:0xf
	v_add_f32_dpp v230, v230, v230 quad_perm:[2,3,0,1] row_mask:0xf bank_mask:0xf
	v_add_f32_dpp v231, v231, v231 quad_perm:[2,3,0,1] row_mask:0xf bank_mask:0xf
	v_add_f32_dpp v232, v232, v232 quad_perm:[2,3,0,1] row_mask:0xf bank_mask:0xf
	v_add_f32_dpp v233, v233, v233 quad_perm:[2,3,0,1] row_mask:0xf bank_mask:0xf
	v_add_f32_dpp v226, v226, v226 row_half_mirror row_mask:0xf bank_mask:0xf
	v_add_f32_dpp v227, v227, v227 row_half_mirror row_mask:0xf bank_mask:0xf
	v_add_f32_dpp v228, v228, v228 row_half_mirror row_mask:0xf bank_mask:0xf
	v_add_f32_dpp v229, v229, v229 row_half_mirror row_mask:0xf bank_mask:0xf
	v_add_f32_dpp v230, v230, v230 row_half_mirror row_mask:0xf bank_mask:0xf
	v_add_f32_dpp v231, v231, v231 row_half_mirror row_mask:0xf bank_mask:0xf
	v_add_f32_dpp v232, v232, v232 row_half_mirror row_mask:0xf bank_mask:0xf
	v_add_f32_dpp v233, v233, v233 row_half_mirror row_mask:0xf bank_mask:0xf
	v_add_f32_dpp v226, v226, v226 row_mirror row_mask:0xf bank_mask:0xf
	v_add_f32_dpp v227, v227, v227 row_mirror row_mask:0xf bank_mask:0xf
	v_add_f32_dpp v228, v228, v228 row_mirror row_mask:0xf bank_mask:0xf
	v_add_f32_dpp v229, v229, v229 row_mirror row_mask:0xf bank_mask:0xf
	v_add_f32_dpp v230, v230, v230 row_mirror row_mask:0xf bank_mask:0xf
	v_add_f32_dpp v231, v231, v231 row_mirror row_mask:0xf bank_mask:0xf
	v_add_f32_dpp v232, v232, v232 row_mirror row_mask:0xf bank_mask:0xf
	v_add_f32_dpp v233, v233, v233 row_mirror row_mask:0xf bank_mask:0xf
	v_add_f32_dpp v226, v226, v226 row_bcast:15 row_mask:0xa bank_mask:0xf
	v_add_f32_dpp v227, v227, v227 row_bcast:15 row_mask:0xa bank_mask:0xf
	v_add_f32_dpp v228, v228, v228 row_bcast:15 row_mask:0xa bank_mask:0xf
	v_add_f32_dpp v229, v229, v229 row_bcast:15 row_mask:0xa bank_mask:0xf
	v_add_f32_dpp v230, v230, v230 row_bcast:15 row_mask:0xa bank_mask:0xf
	v_add_f32_dpp v231, v231, v231 row_bcast:15 row_mask:0xa bank_mask:0xf
	v_add_f32_dpp v232, v232, v232 row_bcast:15 row_mask:0xa bank_mask:0xf
	v_add_f32_dpp v233, v233, v233 row_bcast:15 row_mask:0xa bank_mask:0xf
	v_add_f32_dpp v226, v226, v226 row_bcast:31 row_mask:0xc bank_mask:0xf
	v_add_f32_dpp v227, v227, v227 row_bcast:31 row_mask:0xc bank_mask:0xf
	v_add_f32_dpp v228, v228, v228 row_bcast:31 row_mask:0xc bank_mask:0xf
	v_add_f32_dpp v229, v229, v229 row_bcast:31 row_mask:0xc bank_mask:0xf
	v_add_f32_dpp v230, v230, v230 row_bcast:31 row_mask:0xc bank_mask:0xf
	v_add_f32_dpp v231, v231, v231 row_bcast:31 row_mask:0xc bank_mask:0xf
	v_add_f32_dpp v232, v232, v232 row_bcast:31 row_mask:0xc bank_mask:0xf
	v_add_f32_dpp v233, v233, v233 row_bcast:31 row_mask:0xc bank_mask:0xf
	v_readlane_b32 s44, v226, 63
	v_readlane_b32 s45, v227, 63
	v_readlane_b32 s46, v228, 63
	v_readlane_b32 s47, v229, 63
	v_readlane_b32 s48, v230, 63
	v_readlane_b32 s49, v231, 63
	v_readlane_b32 s50, v232, 63
	v_readlane_b32 s51, v233, 63
	s_nop 3
	v_mov_b32_e32 v250, s44
	v_mov_b32_e32 v251, s45
	v_mov_b32_e32 v252, s46
	v_mov_b32_e32 v253, s47
	v_add_f32_e32 v250, s52, v250
	v_add_f32_e32 v251, s53, v251
	v_add_f32_e32 v252, s54, v252
	v_add_f32_e32 v253, s55, v253
	s_mov_b64 exec, 1
	global_store_dwordx4 v246, v[250:253], s[30:31]
	s_nop 1
	v_mov_b32_e32 v250, s48
	v_mov_b32_e32 v251, s49
	v_mov_b32_e32 v252, s50
	v_mov_b32_e32 v253, s51
	v_add_f32_e32 v250, s56, v250
	v_add_f32_e32 v251, s57, v251
	v_add_f32_e32 v252, s58, v252
	v_add_f32_e32 v253, s59, v253
	global_store_dwordx4 v246, v[250:253], s[30:31] offset:16
	s_mov_b64 exec, -1
	s_add_u32 s26, s8, 0x2800000
	s_addc_u32 s27, s9, 0
	global_load_dwordx4 v[144:147], v246, s[26:27]
	global_load_dwordx4 v[148:151], v246, s[26:27] offset:1024
	global_load_dwordx4 v[152:155], v246, s[26:27] offset:2048
	global_load_dwordx4 v[156:159], v246, s[26:27] offset:3072
	s_waitcnt vmcnt(24)
	v_add_f32_e32 v234, v160, v161
	v_mul_f32_e32 v235, v160, v160
	v_add_f32_e32 v238, v162, v163
	v_mul_f32_e32 v239, v161, v161
	v_fmac_f32_e32 v235, v162, v162
	v_fmac_f32_e32 v239, v163, v163
	v_fmac_f32_e32 v235, v164, v164
	v_fmac_f32_e32 v239, v165, v165
	v_add_f32_e32 v234, v234, v164
	v_add_f32_e32 v238, v238, v165
	v_fmac_f32_e32 v235, v166, v166
	v_fmac_f32_e32 v239, v167, v167
	v_add_f32_e32 v234, v234, v166
	v_add_f32_e32 v238, v238, v167
	v_fmac_f32_e32 v235, v168, v168
	v_fmac_f32_e32 v239, v169, v169
	v_add_f32_e32 v234, v234, v168
	v_add_f32_e32 v238, v238, v169
	v_fmac_f32_e32 v235, v170, v170
	v_fmac_f32_e32 v239, v171, v171
	v_add_f32_e32 v234, v234, v170
	v_add_f32_e32 v238, v238, v171
	v_fmac_f32_e32 v235, v172, v172
	v_fmac_f32_e32 v239, v173, v173
	v_add_f32_e32 v234, v234, v172
	v_add_f32_e32 v238, v238, v173
	v_fmac_f32_e32 v235, v174, v174
	v_fmac_f32_e32 v239, v175, v175
	v_add_f32_e32 v234, v234, v174
	v_add_f32_e32 v238, v238, v175
	v_add_f32_e32 v234, v234, v238
	v_add_f32_e32 v235, v235, v239
	s_nop 1
	v_add_f32_dpp v234, v234, v234 quad_perm:[1,0,3,2] row_mask:0xf bank_mask:0xf
	v_add_f32_dpp v235, v235, v235 quad_perm:[1,0,3,2] row_mask:0xf bank_mask:0xf
	s_nop 1
	v_add_f32_dpp v234, v234, v234 quad_perm:[2,3,0,1] row_mask:0xf bank_mask:0xf
	v_add_f32_dpp v235, v235, v235 quad_perm:[2,3,0,1] row_mask:0xf bank_mask:0xf
	s_nop 1
	v_add_f32_dpp v234, v234, v234 row_half_mirror row_mask:0xf bank_mask:0xf
	v_add_f32_dpp v235, v235, v235 row_half_mirror row_mask:0xf bank_mask:0xf
	s_nop 1
	v_add_f32_dpp v234, v234, v234 row_mirror row_mask:0xf bank_mask:0xf
	v_add_f32_dpp v235, v235, v235 row_mirror row_mask:0xf bank_mask:0xf
	s_nop 1
	v_add_f32_dpp v234, v234, v234 row_bcast:15 row_mask:0xa bank_mask:0xf
	v_add_f32_dpp v235, v235, v235 row_bcast:15 row_mask:0xa bank_mask:0xf
	s_nop 1
	v_add_f32_dpp v234, v234, v234 row_bcast:31 row_mask:0xc bank_mask:0xf
	v_add_f32_dpp v235, v235, v235 row_bcast:31 row_mask:0xc bank_mask:0xf
	s_nop 1
	v_readlane_b32 s40, v234, 63
	v_readlane_b32 s41, v235, 63
	s_nop 3
	v_mov_b32_e32 v238, s40
	v_mov_b32_e32 v239, s41
	v_mul_f32_e32 v236, s39, v238
	v_mul_f32_e32 v239, s39, v239
	v_fma_f32 v239, -v236, v236, v239
	v_max_f32_e32 v239, 0x0, v239
	v_add_f32_e32 v239, 0x3727c5ac, v239
	v_rsq_f32_e32 v237, v239
	v_sub_f32_e32 v160, v160, v236
	v_sub_f32_e32 v161, v161, v236
	v_sub_f32_e32 v162, v162, v236
	v_sub_f32_e32 v163, v163, v236
	v_sub_f32_e32 v164, v164, v236
	v_sub_f32_e32 v165, v165, v236
	v_sub_f32_e32 v166, v166, v236
	v_sub_f32_e32 v167, v167, v236
	v_sub_f32_e32 v168, v168, v236
	v_sub_f32_e32 v169, v169, v236
	v_sub_f32_e32 v170, v170, v236
	v_sub_f32_e32 v171, v171, v236
	v_sub_f32_e32 v172, v172, v236
	v_sub_f32_e32 v173, v173, v236
	v_sub_f32_e32 v174, v174, v236
	v_sub_f32_e32 v175, v175, v236
	v_mul_f32_e32 v160, v160, v237
	v_mul_f32_e32 v161, v161, v237
	v_mul_f32_e32 v162, v162, v237
	v_mul_f32_e32 v163, v163, v237
	v_mul_f32_e32 v164, v164, v237
	v_mul_f32_e32 v165, v165, v237
	v_mul_f32_e32 v166, v166, v237
	v_mul_f32_e32 v167, v167, v237
	v_mul_f32_e32 v168, v168, v237
	v_mul_f32_e32 v169, v169, v237
	v_mul_f32_e32 v170, v170, v237
	v_mul_f32_e32 v171, v171, v237
	v_mul_f32_e32 v172, v172, v237
	v_mul_f32_e32 v173, v173, v237
	v_mul_f32_e32 v174, v174, v237
	v_mul_f32_e32 v175, v175, v237
	v_fma_f32 v160, v160, v210, v194
	v_fma_f32 v161, v161, v211, v195
	v_fma_f32 v162, v162, v212, v196
	v_fma_f32 v163, v163, v213, v197
	v_fma_f32 v164, v164, v214, v198
	v_fma_f32 v165, v165, v215, v199
	v_fma_f32 v166, v166, v216, v200
	v_fma_f32 v167, v167, v217, v201
	v_fma_f32 v168, v168, v218, v202
	v_fma_f32 v169, v169, v219, v203
	v_fma_f32 v170, v170, v220, v204
	v_fma_f32 v171, v171, v221, v205
	v_fma_f32 v172, v172, v222, v206
	v_fma_f32 v173, v173, v223, v207
	v_fma_f32 v174, v174, v224, v208
	v_fma_f32 v175, v175, v225, v209
	s_add_u32 s28, s14, 0x800000
	s_addc_u32 s29, s15, 0
	s_add_u32 s30, s22, 0x20000
	s_addc_u32 s31, s23, 0
	v_cvt_pk_bf16_f32 v238, v160, v161
	v_cvt_pk_bf16_f32 v239, v162, v163
	global_store_dwordx2 v247, v[238:239], s[28:29]
	v_cvt_pk_bf16_f32 v240, v164, v165
	v_cvt_pk_bf16_f32 v241, v166, v167
	global_store_dwordx2 v247, v[240:241], s[28:29] offset:512
	s_nop 0
	v_cvt_pk_bf16_f32 v238, v168, v169
	v_cvt_pk_bf16_f32 v239, v170, v171
	global_store_dwordx2 v247, v[238:239], s[28:29] offset:1024
	v_cvt_pk_bf16_f32 v240, v172, v173
	v_cvt_pk_bf16_f32 v241, v174, v175
	global_store_dwordx2 v247, v[240:241], s[28:29] offset:1536
	v_mul_f32_e32 v226, v160, v0
	v_mul_f32_e32 v227, v160, v16
	v_mul_f32_e32 v228, v160, v32
	v_mul_f32_e32 v229, v160, v48
	v_mul_f32_e32 v230, v160, v64
	v_mul_f32_e32 v231, v160, v80
	v_mul_f32_e32 v232, v160, v96
	v_mul_f32_e32 v233, v160, v112
	v_fmac_f32_e32 v226, v161, v1
	v_fmac_f32_e32 v227, v161, v17
	v_fmac_f32_e32 v228, v161, v33
	v_fmac_f32_e32 v229, v161, v49
	v_fmac_f32_e32 v230, v161, v65
	v_fmac_f32_e32 v231, v161, v81
	v_fmac_f32_e32 v232, v161, v97
	v_fmac_f32_e32 v233, v161, v113
	v_fmac_f32_e32 v226, v162, v2
	v_fmac_f32_e32 v227, v162, v18
	v_fmac_f32_e32 v228, v162, v34
	v_fmac_f32_e32 v229, v162, v50
	v_fmac_f32_e32 v230, v162, v66
	v_fmac_f32_e32 v231, v162, v82
	v_fmac_f32_e32 v232, v162, v98
	v_fmac_f32_e32 v233, v162, v114
	v_fmac_f32_e32 v226, v163, v3
	v_fmac_f32_e32 v227, v163, v19
	v_fmac_f32_e32 v228, v163, v35
	v_fmac_f32_e32 v229, v163, v51
	v_fmac_f32_e32 v230, v163, v67
	v_fmac_f32_e32 v231, v163, v83
	v_fmac_f32_e32 v232, v163, v99
	v_fmac_f32_e32 v233, v163, v115
	v_fmac_f32_e32 v226, v164, v4
	v_fmac_f32_e32 v227, v164, v20
	v_fmac_f32_e32 v228, v164, v36
	v_fmac_f32_e32 v229, v164, v52
	v_fmac_f32_e32 v230, v164, v68
	v_fmac_f32_e32 v231, v164, v84
	v_fmac_f32_e32 v232, v164, v100
	v_fmac_f32_e32 v233, v164, v116
	v_fmac_f32_e32 v226, v165, v5
	v_fmac_f32_e32 v227, v165, v21
	v_fmac_f32_e32 v228, v165, v37
	v_fmac_f32_e32 v229, v165, v53
	v_fmac_f32_e32 v230, v165, v69
	v_fmac_f32_e32 v231, v165, v85
	v_fmac_f32_e32 v232, v165, v101
	v_fmac_f32_e32 v233, v165, v117
	v_fmac_f32_e32 v226, v166, v6
	v_fmac_f32_e32 v227, v166, v22
	v_fmac_f32_e32 v228, v166, v38
	v_fmac_f32_e32 v229, v166, v54
	v_fmac_f32_e32 v230, v166, v70
	v_fmac_f32_e32 v231, v166, v86
	v_fmac_f32_e32 v232, v166, v102
	v_fmac_f32_e32 v233, v166, v118
	v_fmac_f32_e32 v226, v167, v7
	v_fmac_f32_e32 v227, v167, v23
	v_fmac_f32_e32 v228, v167, v39
	v_fmac_f32_e32 v229, v167, v55
	v_fmac_f32_e32 v230, v167, v71
	v_fmac_f32_e32 v231, v167, v87
	v_fmac_f32_e32 v232, v167, v103
	v_fmac_f32_e32 v233, v167, v119
	v_fmac_f32_e32 v226, v168, v8
	v_fmac_f32_e32 v227, v168, v24
	v_fmac_f32_e32 v228, v168, v40
	v_fmac_f32_e32 v229, v168, v56
	v_fmac_f32_e32 v230, v168, v72
	v_fmac_f32_e32 v231, v168, v88
	v_fmac_f32_e32 v232, v168, v104
	v_fmac_f32_e32 v233, v168, v120
	v_fmac_f32_e32 v226, v169, v9
	v_fmac_f32_e32 v227, v169, v25
	v_fmac_f32_e32 v228, v169, v41
	v_fmac_f32_e32 v229, v169, v57
	v_fmac_f32_e32 v230, v169, v73
	v_fmac_f32_e32 v231, v169, v89
	v_fmac_f32_e32 v232, v169, v105
	v_fmac_f32_e32 v233, v169, v121
	v_fmac_f32_e32 v226, v170, v10
	v_fmac_f32_e32 v227, v170, v26
	v_fmac_f32_e32 v228, v170, v42
	v_fmac_f32_e32 v229, v170, v58
	v_fmac_f32_e32 v230, v170, v74
	v_fmac_f32_e32 v231, v170, v90
	v_fmac_f32_e32 v232, v170, v106
	v_fmac_f32_e32 v233, v170, v122
	v_fmac_f32_e32 v226, v171, v11
	v_fmac_f32_e32 v227, v171, v27
	v_fmac_f32_e32 v228, v171, v43
	v_fmac_f32_e32 v229, v171, v59
	v_fmac_f32_e32 v230, v171, v75
	v_fmac_f32_e32 v231, v171, v91
	v_fmac_f32_e32 v232, v171, v107
	v_fmac_f32_e32 v233, v171, v123
	v_fmac_f32_e32 v226, v172, v12
	v_fmac_f32_e32 v227, v172, v28
	v_fmac_f32_e32 v228, v172, v44
	v_fmac_f32_e32 v229, v172, v60
	v_fmac_f32_e32 v230, v172, v76
	v_fmac_f32_e32 v231, v172, v92
	v_fmac_f32_e32 v232, v172, v108
	v_fmac_f32_e32 v233, v172, v124
	v_fmac_f32_e32 v226, v173, v13
	v_fmac_f32_e32 v227, v173, v29
	v_fmac_f32_e32 v228, v173, v45
	v_fmac_f32_e32 v229, v173, v61
	v_fmac_f32_e32 v230, v173, v77
	v_fmac_f32_e32 v231, v173, v93
	v_fmac_f32_e32 v232, v173, v109
	v_fmac_f32_e32 v233, v173, v125
	v_fmac_f32_e32 v226, v174, v14
	v_fmac_f32_e32 v227, v174, v30
	v_fmac_f32_e32 v228, v174, v46
	v_fmac_f32_e32 v229, v174, v62
	v_fmac_f32_e32 v230, v174, v78
	v_fmac_f32_e32 v231, v174, v94
	v_fmac_f32_e32 v232, v174, v110
	v_fmac_f32_e32 v233, v174, v126
	v_fmac_f32_e32 v226, v175, v15
	v_fmac_f32_e32 v227, v175, v31
	v_fmac_f32_e32 v228, v175, v47
	v_fmac_f32_e32 v229, v175, v63
	v_fmac_f32_e32 v230, v175, v79
	v_fmac_f32_e32 v231, v175, v95
	v_fmac_f32_e32 v232, v175, v111
	v_fmac_f32_e32 v233, v175, v127
	v_add_f32_dpp v226, v226, v226 quad_perm:[1,0,3,2] row_mask:0xf bank_mask:0xf
	v_add_f32_dpp v227, v227, v227 quad_perm:[1,0,3,2] row_mask:0xf bank_mask:0xf
	v_add_f32_dpp v228, v228, v228 quad_perm:[1,0,3,2] row_mask:0xf bank_mask:0xf
	v_add_f32_dpp v229, v229, v229 quad_perm:[1,0,3,2] row_mask:0xf bank_mask:0xf
	v_add_f32_dpp v230, v230, v230 quad_perm:[1,0,3,2] row_mask:0xf bank_mask:0xf
	v_add_f32_dpp v231, v231, v231 quad_perm:[1,0,3,2] row_mask:0xf bank_mask:0xf
	v_add_f32_dpp v232, v232, v232 quad_perm:[1,0,3,2] row_mask:0xf bank_mask:0xf
	v_add_f32_dpp v233, v233, v233 quad_perm:[1,0,3,2] row_mask:0xf bank_mask:0xf
	v_add_f32_dpp v226, v226, v226 quad_perm:[2,3,0,1] row_mask:0xf bank_mask:0xf
	v_add_f32_dpp v227, v227, v227 quad_perm:[2,3,0,1] row_mask:0xf bank_mask:0xf
	v_add_f32_dpp v228, v228, v228 quad_perm:[2,3,0,1] row_mask:0xf bank_mask:0xf
	v_add_f32_dpp v229, v229, v229 quad_perm:[2,3,0,1] row_mask:0xf bank_mask:0xf
	v_add_f32_dpp v230, v230, v230 quad_perm:[2,3,0,1] row_mask:0xf bank_mask:0xf
	v_add_f32_dpp v231, v231, v231 quad_perm:[2,3,0,1] row_mask:0xf bank_mask:0xf
	v_add_f32_dpp v232, v232, v232 quad_perm:[2,3,0,1] row_mask:0xf bank_mask:0xf
	v_add_f32_dpp v233, v233, v233 quad_perm:[2,3,0,1] row_mask:0xf bank_mask:0xf
	v_add_f32_dpp v226, v226, v226 row_half_mirror row_mask:0xf bank_mask:0xf
	v_add_f32_dpp v227, v227, v227 row_half_mirror row_mask:0xf bank_mask:0xf
	v_add_f32_dpp v228, v228, v228 row_half_mirror row_mask:0xf bank_mask:0xf
	v_add_f32_dpp v229, v229, v229 row_half_mirror row_mask:0xf bank_mask:0xf
	v_add_f32_dpp v230, v230, v230 row_half_mirror row_mask:0xf bank_mask:0xf
	v_add_f32_dpp v231, v231, v231 row_half_mirror row_mask:0xf bank_mask:0xf
	v_add_f32_dpp v232, v232, v232 row_half_mirror row_mask:0xf bank_mask:0xf
	v_add_f32_dpp v233, v233, v233 row_half_mirror row_mask:0xf bank_mask:0xf
	v_add_f32_dpp v226, v226, v226 row_mirror row_mask:0xf bank_mask:0xf
	v_add_f32_dpp v227, v227, v227 row_mirror row_mask:0xf bank_mask:0xf
	v_add_f32_dpp v228, v228, v228 row_mirror row_mask:0xf bank_mask:0xf
	v_add_f32_dpp v229, v229, v229 row_mirror row_mask:0xf bank_mask:0xf
	v_add_f32_dpp v230, v230, v230 row_mirror row_mask:0xf bank_mask:0xf
	v_add_f32_dpp v231, v231, v231 row_mirror row_mask:0xf bank_mask:0xf
	v_add_f32_dpp v232, v232, v232 row_mirror row_mask:0xf bank_mask:0xf
	v_add_f32_dpp v233, v233, v233 row_mirror row_mask:0xf bank_mask:0xf
	v_add_f32_dpp v226, v226, v226 row_bcast:15 row_mask:0xa bank_mask:0xf
	v_add_f32_dpp v227, v227, v227 row_bcast:15 row_mask:0xa bank_mask:0xf
	v_add_f32_dpp v228, v228, v228 row_bcast:15 row_mask:0xa bank_mask:0xf
	v_add_f32_dpp v229, v229, v229 row_bcast:15 row_mask:0xa bank_mask:0xf
	v_add_f32_dpp v230, v230, v230 row_bcast:15 row_mask:0xa bank_mask:0xf
	v_add_f32_dpp v231, v231, v231 row_bcast:15 row_mask:0xa bank_mask:0xf
	v_add_f32_dpp v232, v232, v232 row_bcast:15 row_mask:0xa bank_mask:0xf
	v_add_f32_dpp v233, v233, v233 row_bcast:15 row_mask:0xa bank_mask:0xf
	v_add_f32_dpp v226, v226, v226 row_bcast:31 row_mask:0xc bank_mask:0xf
	v_add_f32_dpp v227, v227, v227 row_bcast:31 row_mask:0xc bank_mask:0xf
	v_add_f32_dpp v228, v228, v228 row_bcast:31 row_mask:0xc bank_mask:0xf
	v_add_f32_dpp v229, v229, v229 row_bcast:31 row_mask:0xc bank_mask:0xf
	v_add_f32_dpp v230, v230, v230 row_bcast:31 row_mask:0xc bank_mask:0xf
	v_add_f32_dpp v231, v231, v231 row_bcast:31 row_mask:0xc bank_mask:0xf
	v_add_f32_dpp v232, v232, v232 row_bcast:31 row_mask:0xc bank_mask:0xf
	v_add_f32_dpp v233, v233, v233 row_bcast:31 row_mask:0xc bank_mask:0xf
	v_readlane_b32 s44, v226, 63
	v_readlane_b32 s45, v227, 63
	v_readlane_b32 s46, v228, 63
	v_readlane_b32 s47, v229, 63
	v_readlane_b32 s48, v230, 63
	v_readlane_b32 s49, v231, 63
	v_readlane_b32 s50, v232, 63
	v_readlane_b32 s51, v233, 63
	s_nop 3
	v_mov_b32_e32 v250, s44
	v_mov_b32_e32 v251, s45
	v_mov_b32_e32 v252, s46
	v_mov_b32_e32 v253, s47
	v_add_f32_e32 v250, s52, v250
	v_add_f32_e32 v251, s53, v251
	v_add_f32_e32 v252, s54, v252
	v_add_f32_e32 v253, s55, v253
	s_mov_b64 exec, 1
	global_store_dwordx4 v246, v[250:253], s[30:31]
	s_nop 1
	v_mov_b32_e32 v250, s48
	v_mov_b32_e32 v251, s49
	v_mov_b32_e32 v252, s50
	v_mov_b32_e32 v253, s51
	v_add_f32_e32 v250, s56, v250
	v_add_f32_e32 v251, s57, v251
	v_add_f32_e32 v252, s58, v252
	v_add_f32_e32 v253, s59, v253
	global_store_dwordx4 v246, v[250:253], s[30:31] offset:16
	s_mov_b64 exec, -1
	s_add_u32 s26, s8, 0x3000000
	s_addc_u32 s27, s9, 0
	global_load_dwordx4 v[160:163], v246, s[26:27]
	global_load_dwordx4 v[164:167], v246, s[26:27] offset:1024
	global_load_dwordx4 v[168:171], v246, s[26:27] offset:2048
	global_load_dwordx4 v[172:175], v246, s[26:27] offset:3072
	s_waitcnt vmcnt(30)
	v_add_f32_e32 v234, v176, v177
	v_mul_f32_e32 v235, v176, v176
	v_add_f32_e32 v238, v178, v179
	v_mul_f32_e32 v239, v177, v177
	v_fmac_f32_e32 v235, v178, v178
	v_fmac_f32_e32 v239, v179, v179
	v_fmac_f32_e32 v235, v180, v180
	v_fmac_f32_e32 v239, v181, v181
	v_add_f32_e32 v234, v234, v180
	v_add_f32_e32 v238, v238, v181
	v_fmac_f32_e32 v235, v182, v182
	v_fmac_f32_e32 v239, v183, v183
	v_add_f32_e32 v234, v234, v182
	v_add_f32_e32 v238, v238, v183
	v_fmac_f32_e32 v235, v184, v184
	v_fmac_f32_e32 v239, v185, v185
	v_add_f32_e32 v234, v234, v184
	v_add_f32_e32 v238, v238, v185
	v_fmac_f32_e32 v235, v186, v186
	v_fmac_f32_e32 v239, v187, v187
	v_add_f32_e32 v234, v234, v186
	v_add_f32_e32 v238, v238, v187
	v_fmac_f32_e32 v235, v188, v188
	v_fmac_f32_e32 v239, v189, v189
	v_add_f32_e32 v234, v234, v188
	v_add_f32_e32 v238, v238, v189
	v_fmac_f32_e32 v235, v190, v190
	v_fmac_f32_e32 v239, v191, v191
	v_add_f32_e32 v234, v234, v190
	v_add_f32_e32 v238, v238, v191
	v_add_f32_e32 v234, v234, v238
	v_add_f32_e32 v235, v235, v239
	s_nop 1
	v_add_f32_dpp v234, v234, v234 quad_perm:[1,0,3,2] row_mask:0xf bank_mask:0xf
	v_add_f32_dpp v235, v235, v235 quad_perm:[1,0,3,2] row_mask:0xf bank_mask:0xf
	s_nop 1
	v_add_f32_dpp v234, v234, v234 quad_perm:[2,3,0,1] row_mask:0xf bank_mask:0xf
	v_add_f32_dpp v235, v235, v235 quad_perm:[2,3,0,1] row_mask:0xf bank_mask:0xf
	s_nop 1
	v_add_f32_dpp v234, v234, v234 row_half_mirror row_mask:0xf bank_mask:0xf
	v_add_f32_dpp v235, v235, v235 row_half_mirror row_mask:0xf bank_mask:0xf
	s_nop 1
	v_add_f32_dpp v234, v234, v234 row_mirror row_mask:0xf bank_mask:0xf
	v_add_f32_dpp v235, v235, v235 row_mirror row_mask:0xf bank_mask:0xf
	s_nop 1
	v_add_f32_dpp v234, v234, v234 row_bcast:15 row_mask:0xa bank_mask:0xf
	v_add_f32_dpp v235, v235, v235 row_bcast:15 row_mask:0xa bank_mask:0xf
	s_nop 1
	v_add_f32_dpp v234, v234, v234 row_bcast:31 row_mask:0xc bank_mask:0xf
	v_add_f32_dpp v235, v235, v235 row_bcast:31 row_mask:0xc bank_mask:0xf
	s_nop 1
	v_readlane_b32 s40, v234, 63
	v_readlane_b32 s41, v235, 63
	s_nop 3
	v_mov_b32_e32 v238, s40
	v_mov_b32_e32 v239, s41
	v_mul_f32_e32 v236, s39, v238
	v_mul_f32_e32 v239, s39, v239
	v_fma_f32 v239, -v236, v236, v239
	v_max_f32_e32 v239, 0x0, v239
	v_add_f32_e32 v239, 0x3727c5ac, v239
	v_rsq_f32_e32 v237, v239
	v_sub_f32_e32 v176, v176, v236
	v_sub_f32_e32 v177, v177, v236
	v_sub_f32_e32 v178, v178, v236
	v_sub_f32_e32 v179, v179, v236
	v_sub_f32_e32 v180, v180, v236
	v_sub_f32_e32 v181, v181, v236
	v_sub_f32_e32 v182, v182, v236
	v_sub_f32_e32 v183, v183, v236
	v_sub_f32_e32 v184, v184, v236
	v_sub_f32_e32 v185, v185, v236
	v_sub_f32_e32 v186, v186, v236
	v_sub_f32_e32 v187, v187, v236
	v_sub_f32_e32 v188, v188, v236
	v_sub_f32_e32 v189, v189, v236
	v_sub_f32_e32 v190, v190, v236
	v_sub_f32_e32 v191, v191, v236
	v_mul_f32_e32 v176, v176, v237
	v_mul_f32_e32 v177, v177, v237
	v_mul_f32_e32 v178, v178, v237
	v_mul_f32_e32 v179, v179, v237
	v_mul_f32_e32 v180, v180, v237
	v_mul_f32_e32 v181, v181, v237
	v_mul_f32_e32 v182, v182, v237
	v_mul_f32_e32 v183, v183, v237
	v_mul_f32_e32 v184, v184, v237
	v_mul_f32_e32 v185, v185, v237
	v_mul_f32_e32 v186, v186, v237
	v_mul_f32_e32 v187, v187, v237
	v_mul_f32_e32 v188, v188, v237
	v_mul_f32_e32 v189, v189, v237
	v_mul_f32_e32 v190, v190, v237
	v_mul_f32_e32 v191, v191, v237
	v_fma_f32 v176, v176, v210, v194
	v_fma_f32 v177, v177, v211, v195
	v_fma_f32 v178, v178, v212, v196
	v_fma_f32 v179, v179, v213, v197
	v_fma_f32 v180, v180, v214, v198
	v_fma_f32 v181, v181, v215, v199
	v_fma_f32 v182, v182, v216, v200
	v_fma_f32 v183, v183, v217, v201
	v_fma_f32 v184, v184, v218, v202
	v_fma_f32 v185, v185, v219, v203
	v_fma_f32 v186, v186, v220, v204
	v_fma_f32 v187, v187, v221, v205
	v_fma_f32 v188, v188, v222, v206
	v_fma_f32 v189, v189, v223, v207
	v_fma_f32 v190, v190, v224, v208
	v_fma_f32 v191, v191, v225, v209
	s_add_u32 s34, s18, 0x6000
	s_addc_u32 s35, s19, 0
	s_add_u32 s36, s34, 0x1000
	s_addc_u32 s37, s35, 0
	global_load_dwordx4 v[194:197], v246, s[34:35]
	global_load_dwordx4 v[198:201], v246, s[34:35] offset:1024
	global_load_dwordx4 v[202:205], v246, s[34:35] offset:2048
	global_load_dwordx4 v[206:209], v246, s[34:35] offset:3072
	global_load_dwordx4 v[210:213], v246, s[36:37]
	global_load_dwordx4 v[214:217], v246, s[36:37] offset:1024
	global_load_dwordx4 v[218:221], v246, s[36:37] offset:2048
	global_load_dwordx4 v[222:225], v246, s[36:37] offset:3072
	s_add_u32 s28, s14, 0xc00000
	s_addc_u32 s29, s15, 0
	s_add_u32 s30, s22, 0x30000
	s_addc_u32 s31, s23, 0
	v_cvt_pk_bf16_f32 v238, v176, v177
	v_cvt_pk_bf16_f32 v239, v178, v179
	global_store_dwordx2 v247, v[238:239], s[28:29]
	v_cvt_pk_bf16_f32 v240, v180, v181
	v_cvt_pk_bf16_f32 v241, v182, v183
	global_store_dwordx2 v247, v[240:241], s[28:29] offset:512
	s_nop 0
	v_cvt_pk_bf16_f32 v238, v184, v185
	v_cvt_pk_bf16_f32 v239, v186, v187
	global_store_dwordx2 v247, v[238:239], s[28:29] offset:1024
	v_cvt_pk_bf16_f32 v240, v188, v189
	v_cvt_pk_bf16_f32 v241, v190, v191
	global_store_dwordx2 v247, v[240:241], s[28:29] offset:1536
	v_mul_f32_e32 v226, v176, v0
	v_mul_f32_e32 v227, v176, v16
	v_mul_f32_e32 v228, v176, v32
	v_mul_f32_e32 v229, v176, v48
	v_mul_f32_e32 v230, v176, v64
	v_mul_f32_e32 v231, v176, v80
	v_mul_f32_e32 v232, v176, v96
	v_mul_f32_e32 v233, v176, v112
	v_fmac_f32_e32 v226, v177, v1
	v_fmac_f32_e32 v227, v177, v17
	v_fmac_f32_e32 v228, v177, v33
	v_fmac_f32_e32 v229, v177, v49
	v_fmac_f32_e32 v230, v177, v65
	v_fmac_f32_e32 v231, v177, v81
	v_fmac_f32_e32 v232, v177, v97
	v_fmac_f32_e32 v233, v177, v113
	v_fmac_f32_e32 v226, v178, v2
	v_fmac_f32_e32 v227, v178, v18
	v_fmac_f32_e32 v228, v178, v34
	v_fmac_f32_e32 v229, v178, v50
	v_fmac_f32_e32 v230, v178, v66
	v_fmac_f32_e32 v231, v178, v82
	v_fmac_f32_e32 v232, v178, v98
	v_fmac_f32_e32 v233, v178, v114
	v_fmac_f32_e32 v226, v179, v3
	v_fmac_f32_e32 v227, v179, v19
	v_fmac_f32_e32 v228, v179, v35
	v_fmac_f32_e32 v229, v179, v51
	v_fmac_f32_e32 v230, v179, v67
	v_fmac_f32_e32 v231, v179, v83
	v_fmac_f32_e32 v232, v179, v99
	v_fmac_f32_e32 v233, v179, v115
	v_fmac_f32_e32 v226, v180, v4
	v_fmac_f32_e32 v227, v180, v20
	v_fmac_f32_e32 v228, v180, v36
	v_fmac_f32_e32 v229, v180, v52
	v_fmac_f32_e32 v230, v180, v68
	v_fmac_f32_e32 v231, v180, v84
	v_fmac_f32_e32 v232, v180, v100
	v_fmac_f32_e32 v233, v180, v116
	v_fmac_f32_e32 v226, v181, v5
	v_fmac_f32_e32 v227, v181, v21
	v_fmac_f32_e32 v228, v181, v37
	v_fmac_f32_e32 v229, v181, v53
	v_fmac_f32_e32 v230, v181, v69
	v_fmac_f32_e32 v231, v181, v85
	v_fmac_f32_e32 v232, v181, v101
	v_fmac_f32_e32 v233, v181, v117
	v_fmac_f32_e32 v226, v182, v6
	v_fmac_f32_e32 v227, v182, v22
	v_fmac_f32_e32 v228, v182, v38
	v_fmac_f32_e32 v229, v182, v54
	v_fmac_f32_e32 v230, v182, v70
	v_fmac_f32_e32 v231, v182, v86
	v_fmac_f32_e32 v232, v182, v102
	v_fmac_f32_e32 v233, v182, v118
	v_fmac_f32_e32 v226, v183, v7
	v_fmac_f32_e32 v227, v183, v23
	v_fmac_f32_e32 v228, v183, v39
	v_fmac_f32_e32 v229, v183, v55
	v_fmac_f32_e32 v230, v183, v71
	v_fmac_f32_e32 v231, v183, v87
	v_fmac_f32_e32 v232, v183, v103
	v_fmac_f32_e32 v233, v183, v119
	v_fmac_f32_e32 v226, v184, v8
	v_fmac_f32_e32 v227, v184, v24
	v_fmac_f32_e32 v228, v184, v40
	v_fmac_f32_e32 v229, v184, v56
	v_fmac_f32_e32 v230, v184, v72
	v_fmac_f32_e32 v231, v184, v88
	v_fmac_f32_e32 v232, v184, v104
	v_fmac_f32_e32 v233, v184, v120
	v_fmac_f32_e32 v226, v185, v9
	v_fmac_f32_e32 v227, v185, v25
	v_fmac_f32_e32 v228, v185, v41
	v_fmac_f32_e32 v229, v185, v57
	v_fmac_f32_e32 v230, v185, v73
	v_fmac_f32_e32 v231, v185, v89
	v_fmac_f32_e32 v232, v185, v105
	v_fmac_f32_e32 v233, v185, v121
	v_fmac_f32_e32 v226, v186, v10
	v_fmac_f32_e32 v227, v186, v26
	v_fmac_f32_e32 v228, v186, v42
	v_fmac_f32_e32 v229, v186, v58
	v_fmac_f32_e32 v230, v186, v74
	v_fmac_f32_e32 v231, v186, v90
	v_fmac_f32_e32 v232, v186, v106
	v_fmac_f32_e32 v233, v186, v122
	v_fmac_f32_e32 v226, v187, v11
	v_fmac_f32_e32 v227, v187, v27
	v_fmac_f32_e32 v228, v187, v43
	v_fmac_f32_e32 v229, v187, v59
	v_fmac_f32_e32 v230, v187, v75
	v_fmac_f32_e32 v231, v187, v91
	v_fmac_f32_e32 v232, v187, v107
	v_fmac_f32_e32 v233, v187, v123
	v_fmac_f32_e32 v226, v188, v12
	v_fmac_f32_e32 v227, v188, v28
	v_fmac_f32_e32 v228, v188, v44
	v_fmac_f32_e32 v229, v188, v60
	v_fmac_f32_e32 v230, v188, v76
	v_fmac_f32_e32 v231, v188, v92
	v_fmac_f32_e32 v232, v188, v108
	v_fmac_f32_e32 v233, v188, v124
	v_fmac_f32_e32 v226, v189, v13
	v_fmac_f32_e32 v227, v189, v29
	v_fmac_f32_e32 v228, v189, v45
	v_fmac_f32_e32 v229, v189, v61
	v_fmac_f32_e32 v230, v189, v77
	v_fmac_f32_e32 v231, v189, v93
	v_fmac_f32_e32 v232, v189, v109
	v_fmac_f32_e32 v233, v189, v125
	v_fmac_f32_e32 v226, v190, v14
	v_fmac_f32_e32 v227, v190, v30
	v_fmac_f32_e32 v228, v190, v46
	v_fmac_f32_e32 v229, v190, v62
	v_fmac_f32_e32 v230, v190, v78
	v_fmac_f32_e32 v231, v190, v94
	v_fmac_f32_e32 v232, v190, v110
	v_fmac_f32_e32 v233, v190, v126
	v_fmac_f32_e32 v226, v191, v15
	v_fmac_f32_e32 v227, v191, v31
	v_fmac_f32_e32 v228, v191, v47
	v_fmac_f32_e32 v229, v191, v63
	v_fmac_f32_e32 v230, v191, v79
	v_fmac_f32_e32 v231, v191, v95
	v_fmac_f32_e32 v232, v191, v111
	v_fmac_f32_e32 v233, v191, v127
	v_add_f32_dpp v226, v226, v226 quad_perm:[1,0,3,2] row_mask:0xf bank_mask:0xf
	v_add_f32_dpp v227, v227, v227 quad_perm:[1,0,3,2] row_mask:0xf bank_mask:0xf
	v_add_f32_dpp v228, v228, v228 quad_perm:[1,0,3,2] row_mask:0xf bank_mask:0xf
	v_add_f32_dpp v229, v229, v229 quad_perm:[1,0,3,2] row_mask:0xf bank_mask:0xf
	v_add_f32_dpp v230, v230, v230 quad_perm:[1,0,3,2] row_mask:0xf bank_mask:0xf
	v_add_f32_dpp v231, v231, v231 quad_perm:[1,0,3,2] row_mask:0xf bank_mask:0xf
	v_add_f32_dpp v232, v232, v232 quad_perm:[1,0,3,2] row_mask:0xf bank_mask:0xf
	v_add_f32_dpp v233, v233, v233 quad_perm:[1,0,3,2] row_mask:0xf bank_mask:0xf
	v_add_f32_dpp v226, v226, v226 quad_perm:[2,3,0,1] row_mask:0xf bank_mask:0xf
	v_add_f32_dpp v227, v227, v227 quad_perm:[2,3,0,1] row_mask:0xf bank_mask:0xf
	v_add_f32_dpp v228, v228, v228 quad_perm:[2,3,0,1] row_mask:0xf bank_mask:0xf
	v_add_f32_dpp v229, v229, v229 quad_perm:[2,3,0,1] row_mask:0xf bank_mask:0xf
	v_add_f32_dpp v230, v230, v230 quad_perm:[2,3,0,1] row_mask:0xf bank_mask:0xf
	v_add_f32_dpp v231, v231, v231 quad_perm:[2,3,0,1] row_mask:0xf bank_mask:0xf
	v_add_f32_dpp v232, v232, v232 quad_perm:[2,3,0,1] row_mask:0xf bank_mask:0xf
	v_add_f32_dpp v233, v233, v233 quad_perm:[2,3,0,1] row_mask:0xf bank_mask:0xf
	v_add_f32_dpp v226, v226, v226 row_half_mirror row_mask:0xf bank_mask:0xf
	v_add_f32_dpp v227, v227, v227 row_half_mirror row_mask:0xf bank_mask:0xf
	v_add_f32_dpp v228, v228, v228 row_half_mirror row_mask:0xf bank_mask:0xf
	v_add_f32_dpp v229, v229, v229 row_half_mirror row_mask:0xf bank_mask:0xf
	v_add_f32_dpp v230, v230, v230 row_half_mirror row_mask:0xf bank_mask:0xf
	v_add_f32_dpp v231, v231, v231 row_half_mirror row_mask:0xf bank_mask:0xf
	v_add_f32_dpp v232, v232, v232 row_half_mirror row_mask:0xf bank_mask:0xf
	v_add_f32_dpp v233, v233, v233 row_half_mirror row_mask:0xf bank_mask:0xf
	v_add_f32_dpp v226, v226, v226 row_mirror row_mask:0xf bank_mask:0xf
	v_add_f32_dpp v227, v227, v227 row_mirror row_mask:0xf bank_mask:0xf
	v_add_f32_dpp v228, v228, v228 row_mirror row_mask:0xf bank_mask:0xf
	v_add_f32_dpp v229, v229, v229 row_mirror row_mask:0xf bank_mask:0xf
	v_add_f32_dpp v230, v230, v230 row_mirror row_mask:0xf bank_mask:0xf
	v_add_f32_dpp v231, v231, v231 row_mirror row_mask:0xf bank_mask:0xf
	v_add_f32_dpp v232, v232, v232 row_mirror row_mask:0xf bank_mask:0xf
	v_add_f32_dpp v233, v233, v233 row_mirror row_mask:0xf bank_mask:0xf
	v_add_f32_dpp v226, v226, v226 row_bcast:15 row_mask:0xa bank_mask:0xf
	v_add_f32_dpp v227, v227, v227 row_bcast:15 row_mask:0xa bank_mask:0xf
	v_add_f32_dpp v228, v228, v228 row_bcast:15 row_mask:0xa bank_mask:0xf
	v_add_f32_dpp v229, v229, v229 row_bcast:15 row_mask:0xa bank_mask:0xf
	v_add_f32_dpp v230, v230, v230 row_bcast:15 row_mask:0xa bank_mask:0xf
	v_add_f32_dpp v231, v231, v231 row_bcast:15 row_mask:0xa bank_mask:0xf
	v_add_f32_dpp v232, v232, v232 row_bcast:15 row_mask:0xa bank_mask:0xf
	v_add_f32_dpp v233, v233, v233 row_bcast:15 row_mask:0xa bank_mask:0xf
	v_add_f32_dpp v226, v226, v226 row_bcast:31 row_mask:0xc bank_mask:0xf
	v_add_f32_dpp v227, v227, v227 row_bcast:31 row_mask:0xc bank_mask:0xf
	v_add_f32_dpp v228, v228, v228 row_bcast:31 row_mask:0xc bank_mask:0xf
	v_add_f32_dpp v229, v229, v229 row_bcast:31 row_mask:0xc bank_mask:0xf
	v_add_f32_dpp v230, v230, v230 row_bcast:31 row_mask:0xc bank_mask:0xf
	v_add_f32_dpp v231, v231, v231 row_bcast:31 row_mask:0xc bank_mask:0xf
	v_add_f32_dpp v232, v232, v232 row_bcast:31 row_mask:0xc bank_mask:0xf
	v_add_f32_dpp v233, v233, v233 row_bcast:31 row_mask:0xc bank_mask:0xf
	v_readlane_b32 s44, v226, 63
	v_readlane_b32 s45, v227, 63
	v_readlane_b32 s46, v228, 63
	v_readlane_b32 s47, v229, 63
	v_readlane_b32 s48, v230, 63
	v_readlane_b32 s49, v231, 63
	v_readlane_b32 s50, v232, 63
	v_readlane_b32 s51, v233, 63
	s_nop 3
	v_mov_b32_e32 v250, s44
	v_mov_b32_e32 v251, s45
	v_mov_b32_e32 v252, s46
	v_mov_b32_e32 v253, s47
	v_add_f32_e32 v250, s52, v250
	v_add_f32_e32 v251, s53, v251
	v_add_f32_e32 v252, s54, v252
	v_add_f32_e32 v253, s55, v253
	s_mov_b64 exec, 1
	global_store_dwordx4 v246, v[250:253], s[30:31]
	s_nop 1
	v_mov_b32_e32 v250, s48
	v_mov_b32_e32 v251, s49
	v_mov_b32_e32 v252, s50
	v_mov_b32_e32 v253, s51
	v_add_f32_e32 v250, s56, v250
	v_add_f32_e32 v251, s57, v251
	v_add_f32_e32 v252, s58, v252
	v_add_f32_e32 v253, s59, v253
	global_store_dwordx4 v246, v[250:253], s[30:31] offset:16
	s_mov_b64 exec, -1
	s_add_u32 s26, s8, 0x3800000
	s_addc_u32 s27, s9, 0
	global_load_dwordx4 v[176:179], v246, s[26:27]
	global_load_dwordx4 v[180:183], v246, s[26:27] offset:1024
	global_load_dwordx4 v[184:187], v246, s[26:27] offset:2048
	global_load_dwordx4 v[188:191], v246, s[26:27] offset:3072
	s_waitcnt vmcnt(10)
	v_add_f32_e32 v210, 1.0, v210
	v_add_f32_e32 v211, 1.0, v211
	v_add_f32_e32 v212, 1.0, v212
	v_add_f32_e32 v213, 1.0, v213
	v_add_f32_e32 v214, 1.0, v214
	v_add_f32_e32 v215, 1.0, v215
	v_add_f32_e32 v216, 1.0, v216
	v_add_f32_e32 v217, 1.0, v217
	v_add_f32_e32 v218, 1.0, v218
	v_add_f32_e32 v219, 1.0, v219
	v_add_f32_e32 v220, 1.0, v220
	v_add_f32_e32 v221, 1.0, v221
	v_add_f32_e32 v222, 1.0, v222
	v_add_f32_e32 v223, 1.0, v223
	v_add_f32_e32 v224, 1.0, v224
	v_add_f32_e32 v225, 1.0, v225
	v_add_f32_e32 v234, v128, v129
	v_mul_f32_e32 v235, v128, v128
	v_add_f32_e32 v238, v130, v131
	v_mul_f32_e32 v239, v129, v129
	v_fmac_f32_e32 v235, v130, v130
	v_fmac_f32_e32 v239, v131, v131
	v_fmac_f32_e32 v235, v132, v132
	v_fmac_f32_e32 v239, v133, v133
	v_add_f32_e32 v234, v234, v132
	v_add_f32_e32 v238, v238, v133
	v_fmac_f32_e32 v235, v134, v134
	v_fmac_f32_e32 v239, v135, v135
	v_add_f32_e32 v234, v234, v134
	v_add_f32_e32 v238, v238, v135
	v_fmac_f32_e32 v235, v136, v136
	v_fmac_f32_e32 v239, v137, v137
	v_add_f32_e32 v234, v234, v136
	v_add_f32_e32 v238, v238, v137
	v_fmac_f32_e32 v235, v138, v138
	v_fmac_f32_e32 v239, v139, v139
	v_add_f32_e32 v234, v234, v138
	v_add_f32_e32 v238, v238, v139
	v_fmac_f32_e32 v235, v140, v140
	v_fmac_f32_e32 v239, v141, v141
	v_add_f32_e32 v234, v234, v140
	v_add_f32_e32 v238, v238, v141
	v_fmac_f32_e32 v235, v142, v142
	v_fmac_f32_e32 v239, v143, v143
	v_add_f32_e32 v234, v234, v142
	v_add_f32_e32 v238, v238, v143
	v_add_f32_e32 v234, v234, v238
	v_add_f32_e32 v235, v235, v239
	s_nop 1
	v_add_f32_dpp v234, v234, v234 quad_perm:[1,0,3,2] row_mask:0xf bank_mask:0xf
	v_add_f32_dpp v235, v235, v235 quad_perm:[1,0,3,2] row_mask:0xf bank_mask:0xf
	s_nop 1
	v_add_f32_dpp v234, v234, v234 quad_perm:[2,3,0,1] row_mask:0xf bank_mask:0xf
	v_add_f32_dpp v235, v235, v235 quad_perm:[2,3,0,1] row_mask:0xf bank_mask:0xf
	s_nop 1
	v_add_f32_dpp v234, v234, v234 row_half_mirror row_mask:0xf bank_mask:0xf
	v_add_f32_dpp v235, v235, v235 row_half_mirror row_mask:0xf bank_mask:0xf
	s_nop 1
	v_add_f32_dpp v234, v234, v234 row_mirror row_mask:0xf bank_mask:0xf
	v_add_f32_dpp v235, v235, v235 row_mirror row_mask:0xf bank_mask:0xf
	s_nop 1
	v_add_f32_dpp v234, v234, v234 row_bcast:15 row_mask:0xa bank_mask:0xf
	v_add_f32_dpp v235, v235, v235 row_bcast:15 row_mask:0xa bank_mask:0xf
	s_nop 1
	v_add_f32_dpp v234, v234, v234 row_bcast:31 row_mask:0xc bank_mask:0xf
	v_add_f32_dpp v235, v235, v235 row_bcast:31 row_mask:0xc bank_mask:0xf
	s_nop 1
	v_readlane_b32 s40, v234, 63
	v_readlane_b32 s41, v235, 63
	s_nop 3
	v_mov_b32_e32 v238, s40
	v_mov_b32_e32 v239, s41
	v_mul_f32_e32 v236, s39, v238
	v_mul_f32_e32 v239, s39, v239
	v_fma_f32 v239, -v236, v236, v239
	v_max_f32_e32 v239, 0x0, v239
	v_add_f32_e32 v239, 0x3727c5ac, v239
	v_rsq_f32_e32 v237, v239
	v_sub_f32_e32 v128, v128, v236
	v_sub_f32_e32 v129, v129, v236
	v_sub_f32_e32 v130, v130, v236
	v_sub_f32_e32 v131, v131, v236
	v_sub_f32_e32 v132, v132, v236
	v_sub_f32_e32 v133, v133, v236
	v_sub_f32_e32 v134, v134, v236
	v_sub_f32_e32 v135, v135, v236
	v_sub_f32_e32 v136, v136, v236
	v_sub_f32_e32 v137, v137, v236
	v_sub_f32_e32 v138, v138, v236
	v_sub_f32_e32 v139, v139, v236
	v_sub_f32_e32 v140, v140, v236
	v_sub_f32_e32 v141, v141, v236
	v_sub_f32_e32 v142, v142, v236
	v_sub_f32_e32 v143, v143, v236
	v_mul_f32_e32 v128, v128, v237
	v_mul_f32_e32 v129, v129, v237
	v_mul_f32_e32 v130, v130, v237
	v_mul_f32_e32 v131, v131, v237
	v_mul_f32_e32 v132, v132, v237
	v_mul_f32_e32 v133, v133, v237
	v_mul_f32_e32 v134, v134, v237
	v_mul_f32_e32 v135, v135, v237
	v_mul_f32_e32 v136, v136, v237
	v_mul_f32_e32 v137, v137, v237
	v_mul_f32_e32 v138, v138, v237
	v_mul_f32_e32 v139, v139, v237
	v_mul_f32_e32 v140, v140, v237
	v_mul_f32_e32 v141, v141, v237
	v_mul_f32_e32 v142, v142, v237
	v_mul_f32_e32 v143, v143, v237
	v_fma_f32 v128, v128, v210, v194
	v_fma_f32 v129, v129, v211, v195
	v_fma_f32 v130, v130, v212, v196
	v_fma_f32 v131, v131, v213, v197
	v_fma_f32 v132, v132, v214, v198
	v_fma_f32 v133, v133, v215, v199
	v_fma_f32 v134, v134, v216, v200
	v_fma_f32 v135, v135, v217, v201
	v_fma_f32 v136, v136, v218, v202
	v_fma_f32 v137, v137, v219, v203
	v_fma_f32 v138, v138, v220, v204
	v_fma_f32 v139, v139, v221, v205
	v_fma_f32 v140, v140, v222, v206
	v_fma_f32 v141, v141, v223, v207
	v_fma_f32 v142, v142, v224, v208
	v_fma_f32 v143, v143, v225, v209
	s_add_u32 s28, s14, 0x1000000
	s_addc_u32 s29, s15, 0
	s_add_u32 s30, s22, 0x40000
	s_addc_u32 s31, s23, 0
	v_cvt_pk_bf16_f32 v238, v128, v129
	v_cvt_pk_bf16_f32 v239, v130, v131
	global_store_dwordx2 v247, v[238:239], s[28:29]
	v_cvt_pk_bf16_f32 v240, v132, v133
	v_cvt_pk_bf16_f32 v241, v134, v135
	global_store_dwordx2 v247, v[240:241], s[28:29] offset:512
	s_nop 0
	v_cvt_pk_bf16_f32 v238, v136, v137
	v_cvt_pk_bf16_f32 v239, v138, v139
	global_store_dwordx2 v247, v[238:239], s[28:29] offset:1024
	v_cvt_pk_bf16_f32 v240, v140, v141
	v_cvt_pk_bf16_f32 v241, v142, v143
	global_store_dwordx2 v247, v[240:241], s[28:29] offset:1536
	v_mul_f32_e32 v226, v128, v0
	v_mul_f32_e32 v227, v128, v16
	v_mul_f32_e32 v228, v128, v32
	v_mul_f32_e32 v229, v128, v48
	v_mul_f32_e32 v230, v128, v64
	v_mul_f32_e32 v231, v128, v80
	v_mul_f32_e32 v232, v128, v96
	v_mul_f32_e32 v233, v128, v112
	v_fmac_f32_e32 v226, v129, v1
	v_fmac_f32_e32 v227, v129, v17
	v_fmac_f32_e32 v228, v129, v33
	v_fmac_f32_e32 v229, v129, v49
	v_fmac_f32_e32 v230, v129, v65
	v_fmac_f32_e32 v231, v129, v81
	v_fmac_f32_e32 v232, v129, v97
	v_fmac_f32_e32 v233, v129, v113
	v_fmac_f32_e32 v226, v130, v2
	v_fmac_f32_e32 v227, v130, v18
	v_fmac_f32_e32 v228, v130, v34
	v_fmac_f32_e32 v229, v130, v50
	v_fmac_f32_e32 v230, v130, v66
	v_fmac_f32_e32 v231, v130, v82
	v_fmac_f32_e32 v232, v130, v98
	v_fmac_f32_e32 v233, v130, v114
	v_fmac_f32_e32 v226, v131, v3
	v_fmac_f32_e32 v227, v131, v19
	v_fmac_f32_e32 v228, v131, v35
	v_fmac_f32_e32 v229, v131, v51
	v_fmac_f32_e32 v230, v131, v67
	v_fmac_f32_e32 v231, v131, v83
	v_fmac_f32_e32 v232, v131, v99
	v_fmac_f32_e32 v233, v131, v115
	v_fmac_f32_e32 v226, v132, v4
	v_fmac_f32_e32 v227, v132, v20
	v_fmac_f32_e32 v228, v132, v36
	v_fmac_f32_e32 v229, v132, v52
	v_fmac_f32_e32 v230, v132, v68
	v_fmac_f32_e32 v231, v132, v84
	v_fmac_f32_e32 v232, v132, v100
	v_fmac_f32_e32 v233, v132, v116
	v_fmac_f32_e32 v226, v133, v5
	v_fmac_f32_e32 v227, v133, v21
	v_fmac_f32_e32 v228, v133, v37
	v_fmac_f32_e32 v229, v133, v53
	v_fmac_f32_e32 v230, v133, v69
	v_fmac_f32_e32 v231, v133, v85
	v_fmac_f32_e32 v232, v133, v101
	v_fmac_f32_e32 v233, v133, v117
	v_fmac_f32_e32 v226, v134, v6
	v_fmac_f32_e32 v227, v134, v22
	v_fmac_f32_e32 v228, v134, v38
	v_fmac_f32_e32 v229, v134, v54
	v_fmac_f32_e32 v230, v134, v70
	v_fmac_f32_e32 v231, v134, v86
	v_fmac_f32_e32 v232, v134, v102
	v_fmac_f32_e32 v233, v134, v118
	v_fmac_f32_e32 v226, v135, v7
	v_fmac_f32_e32 v227, v135, v23
	v_fmac_f32_e32 v228, v135, v39
	v_fmac_f32_e32 v229, v135, v55
	v_fmac_f32_e32 v230, v135, v71
	v_fmac_f32_e32 v231, v135, v87
	v_fmac_f32_e32 v232, v135, v103
	v_fmac_f32_e32 v233, v135, v119
	v_fmac_f32_e32 v226, v136, v8
	v_fmac_f32_e32 v227, v136, v24
	v_fmac_f32_e32 v228, v136, v40
	v_fmac_f32_e32 v229, v136, v56
	v_fmac_f32_e32 v230, v136, v72
	v_fmac_f32_e32 v231, v136, v88
	v_fmac_f32_e32 v232, v136, v104
	v_fmac_f32_e32 v233, v136, v120
	v_fmac_f32_e32 v226, v137, v9
	v_fmac_f32_e32 v227, v137, v25
	v_fmac_f32_e32 v228, v137, v41
	v_fmac_f32_e32 v229, v137, v57
	v_fmac_f32_e32 v230, v137, v73
	v_fmac_f32_e32 v231, v137, v89
	v_fmac_f32_e32 v232, v137, v105
	v_fmac_f32_e32 v233, v137, v121
	v_fmac_f32_e32 v226, v138, v10
	v_fmac_f32_e32 v227, v138, v26
	v_fmac_f32_e32 v228, v138, v42
	v_fmac_f32_e32 v229, v138, v58
	v_fmac_f32_e32 v230, v138, v74
	v_fmac_f32_e32 v231, v138, v90
	v_fmac_f32_e32 v232, v138, v106
	v_fmac_f32_e32 v233, v138, v122
	v_fmac_f32_e32 v226, v139, v11
	v_fmac_f32_e32 v227, v139, v27
	v_fmac_f32_e32 v228, v139, v43
	v_fmac_f32_e32 v229, v139, v59
	v_fmac_f32_e32 v230, v139, v75
	v_fmac_f32_e32 v231, v139, v91
	v_fmac_f32_e32 v232, v139, v107
	v_fmac_f32_e32 v233, v139, v123
	v_fmac_f32_e32 v226, v140, v12
	v_fmac_f32_e32 v227, v140, v28
	v_fmac_f32_e32 v228, v140, v44
	v_fmac_f32_e32 v229, v140, v60
	v_fmac_f32_e32 v230, v140, v76
	v_fmac_f32_e32 v231, v140, v92
	v_fmac_f32_e32 v232, v140, v108
	v_fmac_f32_e32 v233, v140, v124
	v_fmac_f32_e32 v226, v141, v13
	v_fmac_f32_e32 v227, v141, v29
	v_fmac_f32_e32 v228, v141, v45
	v_fmac_f32_e32 v229, v141, v61
	v_fmac_f32_e32 v230, v141, v77
	v_fmac_f32_e32 v231, v141, v93
	v_fmac_f32_e32 v232, v141, v109
	v_fmac_f32_e32 v233, v141, v125
	v_fmac_f32_e32 v226, v142, v14
	v_fmac_f32_e32 v227, v142, v30
	v_fmac_f32_e32 v228, v142, v46
	v_fmac_f32_e32 v229, v142, v62
	v_fmac_f32_e32 v230, v142, v78
	v_fmac_f32_e32 v231, v142, v94
	v_fmac_f32_e32 v232, v142, v110
	v_fmac_f32_e32 v233, v142, v126
	v_fmac_f32_e32 v226, v143, v15
	v_fmac_f32_e32 v227, v143, v31
	v_fmac_f32_e32 v228, v143, v47
	v_fmac_f32_e32 v229, v143, v63
	v_fmac_f32_e32 v230, v143, v79
	v_fmac_f32_e32 v231, v143, v95
	v_fmac_f32_e32 v232, v143, v111
	v_fmac_f32_e32 v233, v143, v127
	v_add_f32_dpp v226, v226, v226 quad_perm:[1,0,3,2] row_mask:0xf bank_mask:0xf
	v_add_f32_dpp v227, v227, v227 quad_perm:[1,0,3,2] row_mask:0xf bank_mask:0xf
	v_add_f32_dpp v228, v228, v228 quad_perm:[1,0,3,2] row_mask:0xf bank_mask:0xf
	v_add_f32_dpp v229, v229, v229 quad_perm:[1,0,3,2] row_mask:0xf bank_mask:0xf
	v_add_f32_dpp v230, v230, v230 quad_perm:[1,0,3,2] row_mask:0xf bank_mask:0xf
	v_add_f32_dpp v231, v231, v231 quad_perm:[1,0,3,2] row_mask:0xf bank_mask:0xf
	v_add_f32_dpp v232, v232, v232 quad_perm:[1,0,3,2] row_mask:0xf bank_mask:0xf
	v_add_f32_dpp v233, v233, v233 quad_perm:[1,0,3,2] row_mask:0xf bank_mask:0xf
	v_add_f32_dpp v226, v226, v226 quad_perm:[2,3,0,1] row_mask:0xf bank_mask:0xf
	v_add_f32_dpp v227, v227, v227 quad_perm:[2,3,0,1] row_mask:0xf bank_mask:0xf
	v_add_f32_dpp v228, v228, v228 quad_perm:[2,3,0,1] row_mask:0xf bank_mask:0xf
	v_add_f32_dpp v229, v229, v229 quad_perm:[2,3,0,1] row_mask:0xf bank_mask:0xf
	v_add_f32_dpp v230, v230, v230 quad_perm:[2,3,0,1] row_mask:0xf bank_mask:0xf
	v_add_f32_dpp v231, v231, v231 quad_perm:[2,3,0,1] row_mask:0xf bank_mask:0xf
	v_add_f32_dpp v232, v232, v232 quad_perm:[2,3,0,1] row_mask:0xf bank_mask:0xf
	v_add_f32_dpp v233, v233, v233 quad_perm:[2,3,0,1] row_mask:0xf bank_mask:0xf
	v_add_f32_dpp v226, v226, v226 row_half_mirror row_mask:0xf bank_mask:0xf
	v_add_f32_dpp v227, v227, v227 row_half_mirror row_mask:0xf bank_mask:0xf
	v_add_f32_dpp v228, v228, v228 row_half_mirror row_mask:0xf bank_mask:0xf
	v_add_f32_dpp v229, v229, v229 row_half_mirror row_mask:0xf bank_mask:0xf
	v_add_f32_dpp v230, v230, v230 row_half_mirror row_mask:0xf bank_mask:0xf
	v_add_f32_dpp v231, v231, v231 row_half_mirror row_mask:0xf bank_mask:0xf
	v_add_f32_dpp v232, v232, v232 row_half_mirror row_mask:0xf bank_mask:0xf
	v_add_f32_dpp v233, v233, v233 row_half_mirror row_mask:0xf bank_mask:0xf
	v_add_f32_dpp v226, v226, v226 row_mirror row_mask:0xf bank_mask:0xf
	v_add_f32_dpp v227, v227, v227 row_mirror row_mask:0xf bank_mask:0xf
	v_add_f32_dpp v228, v228, v228 row_mirror row_mask:0xf bank_mask:0xf
	v_add_f32_dpp v229, v229, v229 row_mirror row_mask:0xf bank_mask:0xf
	v_add_f32_dpp v230, v230, v230 row_mirror row_mask:0xf bank_mask:0xf
	v_add_f32_dpp v231, v231, v231 row_mirror row_mask:0xf bank_mask:0xf
	v_add_f32_dpp v232, v232, v232 row_mirror row_mask:0xf bank_mask:0xf
	v_add_f32_dpp v233, v233, v233 row_mirror row_mask:0xf bank_mask:0xf
	v_add_f32_dpp v226, v226, v226 row_bcast:15 row_mask:0xa bank_mask:0xf
	v_add_f32_dpp v227, v227, v227 row_bcast:15 row_mask:0xa bank_mask:0xf
	v_add_f32_dpp v228, v228, v228 row_bcast:15 row_mask:0xa bank_mask:0xf
	v_add_f32_dpp v229, v229, v229 row_bcast:15 row_mask:0xa bank_mask:0xf
	v_add_f32_dpp v230, v230, v230 row_bcast:15 row_mask:0xa bank_mask:0xf
	v_add_f32_dpp v231, v231, v231 row_bcast:15 row_mask:0xa bank_mask:0xf
	v_add_f32_dpp v232, v232, v232 row_bcast:15 row_mask:0xa bank_mask:0xf
	v_add_f32_dpp v233, v233, v233 row_bcast:15 row_mask:0xa bank_mask:0xf
	v_add_f32_dpp v226, v226, v226 row_bcast:31 row_mask:0xc bank_mask:0xf
	v_add_f32_dpp v227, v227, v227 row_bcast:31 row_mask:0xc bank_mask:0xf
	v_add_f32_dpp v228, v228, v228 row_bcast:31 row_mask:0xc bank_mask:0xf
	v_add_f32_dpp v229, v229, v229 row_bcast:31 row_mask:0xc bank_mask:0xf
	v_add_f32_dpp v230, v230, v230 row_bcast:31 row_mask:0xc bank_mask:0xf
	v_add_f32_dpp v231, v231, v231 row_bcast:31 row_mask:0xc bank_mask:0xf
	v_add_f32_dpp v232, v232, v232 row_bcast:31 row_mask:0xc bank_mask:0xf
	v_add_f32_dpp v233, v233, v233 row_bcast:31 row_mask:0xc bank_mask:0xf
	v_readlane_b32 s44, v226, 63
	v_readlane_b32 s45, v227, 63
	v_readlane_b32 s46, v228, 63
	v_readlane_b32 s47, v229, 63
	v_readlane_b32 s48, v230, 63
	v_readlane_b32 s49, v231, 63
	v_readlane_b32 s50, v232, 63
	v_readlane_b32 s51, v233, 63
	s_nop 3
	v_mov_b32_e32 v250, s44
	v_mov_b32_e32 v251, s45
	v_mov_b32_e32 v252, s46
	v_mov_b32_e32 v253, s47
	v_add_f32_e32 v250, s52, v250
	v_add_f32_e32 v251, s53, v251
	v_add_f32_e32 v252, s54, v252
	v_add_f32_e32 v253, s55, v253
	s_mov_b64 exec, 1
	global_store_dwordx4 v246, v[250:253], s[30:31]
	s_nop 1
	v_mov_b32_e32 v250, s48
	v_mov_b32_e32 v251, s49
	v_mov_b32_e32 v252, s50
	v_mov_b32_e32 v253, s51
	v_add_f32_e32 v250, s56, v250
	v_add_f32_e32 v251, s57, v251
	v_add_f32_e32 v252, s58, v252
	v_add_f32_e32 v253, s59, v253
	global_store_dwordx4 v246, v[250:253], s[30:31] offset:16
	s_mov_b64 exec, -1
	s_cmp_gt_u32 s24, 511
	s_cbranch_scc1 .Lp1_no8a
	global_load_dwordx4 v[128:131], v246, s[10:11]
	global_load_dwordx4 v[132:135], v246, s[10:11] offset:1024
	global_load_dwordx4 v[136:139], v246, s[10:11] offset:2048
	global_load_dwordx4 v[140:143], v246, s[10:11] offset:3072
.Lp1_no8a:
	s_waitcnt vmcnt(16)
	v_add_f32_e32 v234, v144, v145
	v_mul_f32_e32 v235, v144, v144
	v_add_f32_e32 v238, v146, v147
	v_mul_f32_e32 v239, v145, v145
	v_fmac_f32_e32 v235, v146, v146
	v_fmac_f32_e32 v239, v147, v147
	v_fmac_f32_e32 v235, v148, v148
	v_fmac_f32_e32 v239, v149, v149
	v_add_f32_e32 v234, v234, v148
	v_add_f32_e32 v238, v238, v149
	v_fmac_f32_e32 v235, v150, v150
	v_fmac_f32_e32 v239, v151, v151
	v_add_f32_e32 v234, v234, v150
	v_add_f32_e32 v238, v238, v151
	v_fmac_f32_e32 v235, v152, v152
	v_fmac_f32_e32 v239, v153, v153
	v_add_f32_e32 v234, v234, v152
	v_add_f32_e32 v238, v238, v153
	v_fmac_f32_e32 v235, v154, v154
	v_fmac_f32_e32 v239, v155, v155
	v_add_f32_e32 v234, v234, v154
	v_add_f32_e32 v238, v238, v155
	v_fmac_f32_e32 v235, v156, v156
	v_fmac_f32_e32 v239, v157, v157
	v_add_f32_e32 v234, v234, v156
	v_add_f32_e32 v238, v238, v157
	v_fmac_f32_e32 v235, v158, v158
	v_fmac_f32_e32 v239, v159, v159
	v_add_f32_e32 v234, v234, v158
	v_add_f32_e32 v238, v238, v159
	v_add_f32_e32 v234, v234, v238
	v_add_f32_e32 v235, v235, v239
	s_nop 1
	v_add_f32_dpp v234, v234, v234 quad_perm:[1,0,3,2] row_mask:0xf bank_mask:0xf
	v_add_f32_dpp v235, v235, v235 quad_perm:[1,0,3,2] row_mask:0xf bank_mask:0xf
	s_nop 1
	v_add_f32_dpp v234, v234, v234 quad_perm:[2,3,0,1] row_mask:0xf bank_mask:0xf
	v_add_f32_dpp v235, v235, v235 quad_perm:[2,3,0,1] row_mask:0xf bank_mask:0xf
	s_nop 1
	v_add_f32_dpp v234, v234, v234 row_half_mirror row_mask:0xf bank_mask:0xf
	v_add_f32_dpp v235, v235, v235 row_half_mirror row_mask:0xf bank_mask:0xf
	s_nop 1
	v_add_f32_dpp v234, v234, v234 row_mirror row_mask:0xf bank_mask:0xf
	v_add_f32_dpp v235, v235, v235 row_mirror row_mask:0xf bank_mask:0xf
	s_nop 1
	v_add_f32_dpp v234, v234, v234 row_bcast:15 row_mask:0xa bank_mask:0xf
	v_add_f32_dpp v235, v235, v235 row_bcast:15 row_mask:0xa bank_mask:0xf
	s_nop 1
	v_add_f32_dpp v234, v234, v234 row_bcast:31 row_mask:0xc bank_mask:0xf
	v_add_f32_dpp v235, v235, v235 row_bcast:31 row_mask:0xc bank_mask:0xf
	s_nop 1
	v_readlane_b32 s40, v234, 63
	v_readlane_b32 s41, v235, 63
	s_nop 3
	v_mov_b32_e32 v238, s40
	v_mov_b32_e32 v239, s41
	v_mul_f32_e32 v236, s39, v238
	v_mul_f32_e32 v239, s39, v239
	v_fma_f32 v239, -v236, v236, v239
	v_max_f32_e32 v239, 0x0, v239
	v_add_f32_e32 v239, 0x3727c5ac, v239
	v_rsq_f32_e32 v237, v239
	v_sub_f32_e32 v144, v144, v236
	v_sub_f32_e32 v145, v145, v236
	v_sub_f32_e32 v146, v146, v236
	v_sub_f32_e32 v147, v147, v236
	v_sub_f32_e32 v148, v148, v236
	v_sub_f32_e32 v149, v149, v236
	v_sub_f32_e32 v150, v150, v236
	v_sub_f32_e32 v151, v151, v236
	v_sub_f32_e32 v152, v152, v236
	v_sub_f32_e32 v153, v153, v236
	v_sub_f32_e32 v154, v154, v236
	v_sub_f32_e32 v155, v155, v236
	v_sub_f32_e32 v156, v156, v236
	v_sub_f32_e32 v157, v157, v236
	v_sub_f32_e32 v158, v158, v236
	v_sub_f32_e32 v159, v159, v236
	v_mul_f32_e32 v144, v144, v237
	v_mul_f32_e32 v145, v145, v237
	v_mul_f32_e32 v146, v146, v237
	v_mul_f32_e32 v147, v147, v237
	v_mul_f32_e32 v148, v148, v237
	v_mul_f32_e32 v149, v149, v237
	v_mul_f32_e32 v150, v150, v237
	v_mul_f32_e32 v151, v151, v237
	v_mul_f32_e32 v152, v152, v237
	v_mul_f32_e32 v153, v153, v237
	v_mul_f32_e32 v154, v154, v237
	v_mul_f32_e32 v155, v155, v237
	v_mul_f32_e32 v156, v156, v237
	v_mul_f32_e32 v157, v157, v237
	v_mul_f32_e32 v158, v158, v237
	v_mul_f32_e32 v159, v159, v237
	v_fma_f32 v144, v144, v210, v194
	v_fma_f32 v145, v145, v211, v195
	v_fma_f32 v146, v146, v212, v196
	v_fma_f32 v147, v147, v213, v197
	v_fma_f32 v148, v148, v214, v198
	v_fma_f32 v149, v149, v215, v199
	v_fma_f32 v150, v150, v216, v200
	v_fma_f32 v151, v151, v217, v201
	v_fma_f32 v152, v152, v218, v202
	v_fma_f32 v153, v153, v219, v203
	v_fma_f32 v154, v154, v220, v204
	v_fma_f32 v155, v155, v221, v205
	v_fma_f32 v156, v156, v222, v206
	v_fma_f32 v157, v157, v223, v207
	v_fma_f32 v158, v158, v224, v208
	v_fma_f32 v159, v159, v225, v209
	s_add_u32 s28, s14, 0x1400000
	s_addc_u32 s29, s15, 0
	s_add_u32 s30, s22, 0x50000
	s_addc_u32 s31, s23, 0
	v_cvt_pk_bf16_f32 v238, v144, v145
	v_cvt_pk_bf16_f32 v239, v146, v147
	global_store_dwordx2 v247, v[238:239], s[28:29]
	v_cvt_pk_bf16_f32 v240, v148, v149
	v_cvt_pk_bf16_f32 v241, v150, v151
	global_store_dwordx2 v247, v[240:241], s[28:29] offset:512
	s_nop 0
	v_cvt_pk_bf16_f32 v238, v152, v153
	v_cvt_pk_bf16_f32 v239, v154, v155
	global_store_dwordx2 v247, v[238:239], s[28:29] offset:1024
	v_cvt_pk_bf16_f32 v240, v156, v157
	v_cvt_pk_bf16_f32 v241, v158, v159
	global_store_dwordx2 v247, v[240:241], s[28:29] offset:1536
	v_mul_f32_e32 v226, v144, v0
	v_mul_f32_e32 v227, v144, v16
	v_mul_f32_e32 v228, v144, v32
	v_mul_f32_e32 v229, v144, v48
	v_mul_f32_e32 v230, v144, v64
	v_mul_f32_e32 v231, v144, v80
	v_mul_f32_e32 v232, v144, v96
	v_mul_f32_e32 v233, v144, v112
	v_fmac_f32_e32 v226, v145, v1
	v_fmac_f32_e32 v227, v145, v17
	v_fmac_f32_e32 v228, v145, v33
	v_fmac_f32_e32 v229, v145, v49
	v_fmac_f32_e32 v230, v145, v65
	v_fmac_f32_e32 v231, v145, v81
	v_fmac_f32_e32 v232, v145, v97
	v_fmac_f32_e32 v233, v145, v113
	v_fmac_f32_e32 v226, v146, v2
	v_fmac_f32_e32 v227, v146, v18
	v_fmac_f32_e32 v228, v146, v34
	v_fmac_f32_e32 v229, v146, v50
	v_fmac_f32_e32 v230, v146, v66
	v_fmac_f32_e32 v231, v146, v82
	v_fmac_f32_e32 v232, v146, v98
	v_fmac_f32_e32 v233, v146, v114
	v_fmac_f32_e32 v226, v147, v3
	v_fmac_f32_e32 v227, v147, v19
	v_fmac_f32_e32 v228, v147, v35
	v_fmac_f32_e32 v229, v147, v51
	v_fmac_f32_e32 v230, v147, v67
	v_fmac_f32_e32 v231, v147, v83
	v_fmac_f32_e32 v232, v147, v99
	v_fmac_f32_e32 v233, v147, v115
	v_fmac_f32_e32 v226, v148, v4
	v_fmac_f32_e32 v227, v148, v20
	v_fmac_f32_e32 v228, v148, v36
	v_fmac_f32_e32 v229, v148, v52
	v_fmac_f32_e32 v230, v148, v68
	v_fmac_f32_e32 v231, v148, v84
	v_fmac_f32_e32 v232, v148, v100
	v_fmac_f32_e32 v233, v148, v116
	v_fmac_f32_e32 v226, v149, v5
	v_fmac_f32_e32 v227, v149, v21
	v_fmac_f32_e32 v228, v149, v37
	v_fmac_f32_e32 v229, v149, v53
	v_fmac_f32_e32 v230, v149, v69
	v_fmac_f32_e32 v231, v149, v85
	v_fmac_f32_e32 v232, v149, v101
	v_fmac_f32_e32 v233, v149, v117
	v_fmac_f32_e32 v226, v150, v6
	v_fmac_f32_e32 v227, v150, v22
	v_fmac_f32_e32 v228, v150, v38
	v_fmac_f32_e32 v229, v150, v54
	v_fmac_f32_e32 v230, v150, v70
	v_fmac_f32_e32 v231, v150, v86
	v_fmac_f32_e32 v232, v150, v102
	v_fmac_f32_e32 v233, v150, v118
	v_fmac_f32_e32 v226, v151, v7
	v_fmac_f32_e32 v227, v151, v23
	v_fmac_f32_e32 v228, v151, v39
	v_fmac_f32_e32 v229, v151, v55
	v_fmac_f32_e32 v230, v151, v71
	v_fmac_f32_e32 v231, v151, v87
	v_fmac_f32_e32 v232, v151, v103
	v_fmac_f32_e32 v233, v151, v119
	v_fmac_f32_e32 v226, v152, v8
	v_fmac_f32_e32 v227, v152, v24
	v_fmac_f32_e32 v228, v152, v40
	v_fmac_f32_e32 v229, v152, v56
	v_fmac_f32_e32 v230, v152, v72
	v_fmac_f32_e32 v231, v152, v88
	v_fmac_f32_e32 v232, v152, v104
	v_fmac_f32_e32 v233, v152, v120
	v_fmac_f32_e32 v226, v153, v9
	v_fmac_f32_e32 v227, v153, v25
	v_fmac_f32_e32 v228, v153, v41
	v_fmac_f32_e32 v229, v153, v57
	v_fmac_f32_e32 v230, v153, v73
	v_fmac_f32_e32 v231, v153, v89
	v_fmac_f32_e32 v232, v153, v105
	v_fmac_f32_e32 v233, v153, v121
	v_fmac_f32_e32 v226, v154, v10
	v_fmac_f32_e32 v227, v154, v26
	v_fmac_f32_e32 v228, v154, v42
	v_fmac_f32_e32 v229, v154, v58
	v_fmac_f32_e32 v230, v154, v74
	v_fmac_f32_e32 v231, v154, v90
	v_fmac_f32_e32 v232, v154, v106
	v_fmac_f32_e32 v233, v154, v122
	v_fmac_f32_e32 v226, v155, v11
	v_fmac_f32_e32 v227, v155, v27
	v_fmac_f32_e32 v228, v155, v43
	v_fmac_f32_e32 v229, v155, v59
	v_fmac_f32_e32 v230, v155, v75
	v_fmac_f32_e32 v231, v155, v91
	v_fmac_f32_e32 v232, v155, v107
	v_fmac_f32_e32 v233, v155, v123
	v_fmac_f32_e32 v226, v156, v12
	v_fmac_f32_e32 v227, v156, v28
	v_fmac_f32_e32 v228, v156, v44
	v_fmac_f32_e32 v229, v156, v60
	v_fmac_f32_e32 v230, v156, v76
	v_fmac_f32_e32 v231, v156, v92
	v_fmac_f32_e32 v232, v156, v108
	v_fmac_f32_e32 v233, v156, v124
	v_fmac_f32_e32 v226, v157, v13
	v_fmac_f32_e32 v227, v157, v29
	v_fmac_f32_e32 v228, v157, v45
	v_fmac_f32_e32 v229, v157, v61
	v_fmac_f32_e32 v230, v157, v77
	v_fmac_f32_e32 v231, v157, v93
	v_fmac_f32_e32 v232, v157, v109
	v_fmac_f32_e32 v233, v157, v125
	v_fmac_f32_e32 v226, v158, v14
	v_fmac_f32_e32 v227, v158, v30
	v_fmac_f32_e32 v228, v158, v46
	v_fmac_f32_e32 v229, v158, v62
	v_fmac_f32_e32 v230, v158, v78
	v_fmac_f32_e32 v231, v158, v94
	v_fmac_f32_e32 v232, v158, v110
	v_fmac_f32_e32 v233, v158, v126
	v_fmac_f32_e32 v226, v159, v15
	v_fmac_f32_e32 v227, v159, v31
	v_fmac_f32_e32 v228, v159, v47
	v_fmac_f32_e32 v229, v159, v63
	v_fmac_f32_e32 v230, v159, v79
	v_fmac_f32_e32 v231, v159, v95
	v_fmac_f32_e32 v232, v159, v111
	v_fmac_f32_e32 v233, v159, v127
	v_add_f32_dpp v226, v226, v226 quad_perm:[1,0,3,2] row_mask:0xf bank_mask:0xf
	v_add_f32_dpp v227, v227, v227 quad_perm:[1,0,3,2] row_mask:0xf bank_mask:0xf
	v_add_f32_dpp v228, v228, v228 quad_perm:[1,0,3,2] row_mask:0xf bank_mask:0xf
	v_add_f32_dpp v229, v229, v229 quad_perm:[1,0,3,2] row_mask:0xf bank_mask:0xf
	v_add_f32_dpp v230, v230, v230 quad_perm:[1,0,3,2] row_mask:0xf bank_mask:0xf
	v_add_f32_dpp v231, v231, v231 quad_perm:[1,0,3,2] row_mask:0xf bank_mask:0xf
	v_add_f32_dpp v232, v232, v232 quad_perm:[1,0,3,2] row_mask:0xf bank_mask:0xf
	v_add_f32_dpp v233, v233, v233 quad_perm:[1,0,3,2] row_mask:0xf bank_mask:0xf
	v_add_f32_dpp v226, v226, v226 quad_perm:[2,3,0,1] row_mask:0xf bank_mask:0xf
	v_add_f32_dpp v227, v227, v227 quad_perm:[2,3,0,1] row_mask:0xf bank_mask:0xf
	v_add_f32_dpp v228, v228, v228 quad_perm:[2,3,0,1] row_mask:0xf bank_mask:0xf
	v_add_f32_dpp v229, v229, v229 quad_perm:[2,3,0,1] row_mask:0xf bank_mask:0xf
	v_add_f32_dpp v230, v230, v230 quad_perm:[2,3,0,1] row_mask:0xf bank_mask:0xf
	v_add_f32_dpp v231, v231, v231 quad_perm:[2,3,0,1] row_mask:0xf bank_mask:0xf
	v_add_f32_dpp v232, v232, v232 quad_perm:[2,3,0,1] row_mask:0xf bank_mask:0xf
	v_add_f32_dpp v233, v233, v233 quad_perm:[2,3,0,1] row_mask:0xf bank_mask:0xf
	v_add_f32_dpp v226, v226, v226 row_half_mirror row_mask:0xf bank_mask:0xf
	v_add_f32_dpp v227, v227, v227 row_half_mirror row_mask:0xf bank_mask:0xf
	v_add_f32_dpp v228, v228, v228 row_half_mirror row_mask:0xf bank_mask:0xf
	v_add_f32_dpp v229, v229, v229 row_half_mirror row_mask:0xf bank_mask:0xf
	v_add_f32_dpp v230, v230, v230 row_half_mirror row_mask:0xf bank_mask:0xf
	v_add_f32_dpp v231, v231, v231 row_half_mirror row_mask:0xf bank_mask:0xf
	v_add_f32_dpp v232, v232, v232 row_half_mirror row_mask:0xf bank_mask:0xf
	v_add_f32_dpp v233, v233, v233 row_half_mirror row_mask:0xf bank_mask:0xf
	v_add_f32_dpp v226, v226, v226 row_mirror row_mask:0xf bank_mask:0xf
	v_add_f32_dpp v227, v227, v227 row_mirror row_mask:0xf bank_mask:0xf
	v_add_f32_dpp v228, v228, v228 row_mirror row_mask:0xf bank_mask:0xf
	v_add_f32_dpp v229, v229, v229 row_mirror row_mask:0xf bank_mask:0xf
	v_add_f32_dpp v230, v230, v230 row_mirror row_mask:0xf bank_mask:0xf
	v_add_f32_dpp v231, v231, v231 row_mirror row_mask:0xf bank_mask:0xf
	v_add_f32_dpp v232, v232, v232 row_mirror row_mask:0xf bank_mask:0xf
	v_add_f32_dpp v233, v233, v233 row_mirror row_mask:0xf bank_mask:0xf
	v_add_f32_dpp v226, v226, v226 row_bcast:15 row_mask:0xa bank_mask:0xf
	v_add_f32_dpp v227, v227, v227 row_bcast:15 row_mask:0xa bank_mask:0xf
	v_add_f32_dpp v228, v228, v228 row_bcast:15 row_mask:0xa bank_mask:0xf
	v_add_f32_dpp v229, v229, v229 row_bcast:15 row_mask:0xa bank_mask:0xf
	v_add_f32_dpp v230, v230, v230 row_bcast:15 row_mask:0xa bank_mask:0xf
	v_add_f32_dpp v231, v231, v231 row_bcast:15 row_mask:0xa bank_mask:0xf
	v_add_f32_dpp v232, v232, v232 row_bcast:15 row_mask:0xa bank_mask:0xf
	v_add_f32_dpp v233, v233, v233 row_bcast:15 row_mask:0xa bank_mask:0xf
	v_add_f32_dpp v226, v226, v226 row_bcast:31 row_mask:0xc bank_mask:0xf
	v_add_f32_dpp v227, v227, v227 row_bcast:31 row_mask:0xc bank_mask:0xf
	v_add_f32_dpp v228, v228, v228 row_bcast:31 row_mask:0xc bank_mask:0xf
	v_add_f32_dpp v229, v229, v229 row_bcast:31 row_mask:0xc bank_mask:0xf
	v_add_f32_dpp v230, v230, v230 row_bcast:31 row_mask:0xc bank_mask:0xf
	v_add_f32_dpp v231, v231, v231 row_bcast:31 row_mask:0xc bank_mask:0xf
	v_add_f32_dpp v232, v232, v232 row_bcast:31 row_mask:0xc bank_mask:0xf
	v_add_f32_dpp v233, v233, v233 row_bcast:31 row_mask:0xc bank_mask:0xf
	v_readlane_b32 s44, v226, 63
	v_readlane_b32 s45, v227, 63
	v_readlane_b32 s46, v228, 63
	v_readlane_b32 s47, v229, 63
	v_readlane_b32 s48, v230, 63
	v_readlane_b32 s49, v231, 63
	v_readlane_b32 s50, v232, 63
	v_readlane_b32 s51, v233, 63
	s_nop 3
	v_mov_b32_e32 v250, s44
	v_mov_b32_e32 v251, s45
	v_mov_b32_e32 v252, s46
	v_mov_b32_e32 v253, s47
	v_add_f32_e32 v250, s52, v250
	v_add_f32_e32 v251, s53, v251
	v_add_f32_e32 v252, s54, v252
	v_add_f32_e32 v253, s55, v253
	s_mov_b64 exec, 1
	global_store_dwordx4 v246, v[250:253], s[30:31]
	s_nop 1
	v_mov_b32_e32 v250, s48
	v_mov_b32_e32 v251, s49
	v_mov_b32_e32 v252, s50
	v_mov_b32_e32 v253, s51
	v_add_f32_e32 v250, s56, v250
	v_add_f32_e32 v251, s57, v251
	v_add_f32_e32 v252, s58, v252
	v_add_f32_e32 v253, s59, v253
	global_store_dwordx4 v246, v[250:253], s[30:31] offset:16
	s_mov_b64 exec, -1
	s_waitcnt vmcnt(22)
	v_add_f32_e32 v234, v160, v161
	v_mul_f32_e32 v235, v160, v160
	v_add_f32_e32 v238, v162, v163
	v_mul_f32_e32 v239, v161, v161
	v_fmac_f32_e32 v235, v162, v162
	v_fmac_f32_e32 v239, v163, v163
	v_fmac_f32_e32 v235, v164, v164
	v_fmac_f32_e32 v239, v165, v165
	v_add_f32_e32 v234, v234, v164
	v_add_f32_e32 v238, v238, v165
	v_fmac_f32_e32 v235, v166, v166
	v_fmac_f32_e32 v239, v167, v167
	v_add_f32_e32 v234, v234, v166
	v_add_f32_e32 v238, v238, v167
	v_fmac_f32_e32 v235, v168, v168
	v_fmac_f32_e32 v239, v169, v169
	v_add_f32_e32 v234, v234, v168
	v_add_f32_e32 v238, v238, v169
	v_fmac_f32_e32 v235, v170, v170
	v_fmac_f32_e32 v239, v171, v171
	v_add_f32_e32 v234, v234, v170
	v_add_f32_e32 v238, v238, v171
	v_fmac_f32_e32 v235, v172, v172
	v_fmac_f32_e32 v239, v173, v173
	v_add_f32_e32 v234, v234, v172
	v_add_f32_e32 v238, v238, v173
	v_fmac_f32_e32 v235, v174, v174
	v_fmac_f32_e32 v239, v175, v175
	v_add_f32_e32 v234, v234, v174
	v_add_f32_e32 v238, v238, v175
	v_add_f32_e32 v234, v234, v238
	v_add_f32_e32 v235, v235, v239
	s_nop 1
	v_add_f32_dpp v234, v234, v234 quad_perm:[1,0,3,2] row_mask:0xf bank_mask:0xf
	v_add_f32_dpp v235, v235, v235 quad_perm:[1,0,3,2] row_mask:0xf bank_mask:0xf
	s_nop 1
	v_add_f32_dpp v234, v234, v234 quad_perm:[2,3,0,1] row_mask:0xf bank_mask:0xf
	v_add_f32_dpp v235, v235, v235 quad_perm:[2,3,0,1] row_mask:0xf bank_mask:0xf
	s_nop 1
	v_add_f32_dpp v234, v234, v234 row_half_mirror row_mask:0xf bank_mask:0xf
	v_add_f32_dpp v235, v235, v235 row_half_mirror row_mask:0xf bank_mask:0xf
	s_nop 1
	v_add_f32_dpp v234, v234, v234 row_mirror row_mask:0xf bank_mask:0xf
	v_add_f32_dpp v235, v235, v235 row_mirror row_mask:0xf bank_mask:0xf
	s_nop 1
	v_add_f32_dpp v234, v234, v234 row_bcast:15 row_mask:0xa bank_mask:0xf
	v_add_f32_dpp v235, v235, v235 row_bcast:15 row_mask:0xa bank_mask:0xf
	s_nop 1
	v_add_f32_dpp v234, v234, v234 row_bcast:31 row_mask:0xc bank_mask:0xf
	v_add_f32_dpp v235, v235, v235 row_bcast:31 row_mask:0xc bank_mask:0xf
	s_nop 1
	v_readlane_b32 s40, v234, 63
	v_readlane_b32 s41, v235, 63
	s_nop 3
	v_mov_b32_e32 v238, s40
	v_mov_b32_e32 v239, s41
	v_mul_f32_e32 v236, s39, v238
	v_mul_f32_e32 v239, s39, v239
	v_fma_f32 v239, -v236, v236, v239
	v_max_f32_e32 v239, 0x0, v239
	v_add_f32_e32 v239, 0x3727c5ac, v239
	v_rsq_f32_e32 v237, v239
	v_sub_f32_e32 v160, v160, v236
	v_sub_f32_e32 v161, v161, v236
	v_sub_f32_e32 v162, v162, v236
	v_sub_f32_e32 v163, v163, v236
	v_sub_f32_e32 v164, v164, v236
	v_sub_f32_e32 v165, v165, v236
	v_sub_f32_e32 v166, v166, v236
	v_sub_f32_e32 v167, v167, v236
	v_sub_f32_e32 v168, v168, v236
	v_sub_f32_e32 v169, v169, v236
	v_sub_f32_e32 v170, v170, v236
	v_sub_f32_e32 v171, v171, v236
	v_sub_f32_e32 v172, v172, v236
	v_sub_f32_e32 v173, v173, v236
	v_sub_f32_e32 v174, v174, v236
	v_sub_f32_e32 v175, v175, v236
	v_mul_f32_e32 v160, v160, v237
	v_mul_f32_e32 v161, v161, v237
	v_mul_f32_e32 v162, v162, v237
	v_mul_f32_e32 v163, v163, v237
	v_mul_f32_e32 v164, v164, v237
	v_mul_f32_e32 v165, v165, v237
	v_mul_f32_e32 v166, v166, v237
	v_mul_f32_e32 v167, v167, v237
	v_mul_f32_e32 v168, v168, v237
	v_mul_f32_e32 v169, v169, v237
	v_mul_f32_e32 v170, v170, v237
	v_mul_f32_e32 v171, v171, v237
	v_mul_f32_e32 v172, v172, v237
	v_mul_f32_e32 v173, v173, v237
	v_mul_f32_e32 v174, v174, v237
	v_mul_f32_e32 v175, v175, v237
	v_fma_f32 v160, v160, v210, v194
	v_fma_f32 v161, v161, v211, v195
	v_fma_f32 v162, v162, v212, v196
	v_fma_f32 v163, v163, v213, v197
	v_fma_f32 v164, v164, v214, v198
	v_fma_f32 v165, v165, v215, v199
	v_fma_f32 v166, v166, v216, v200
	v_fma_f32 v167, v167, v217, v201
	v_fma_f32 v168, v168, v218, v202
	v_fma_f32 v169, v169, v219, v203
	v_fma_f32 v170, v170, v220, v204
	v_fma_f32 v171, v171, v221, v205
	v_fma_f32 v172, v172, v222, v206
	v_fma_f32 v173, v173, v223, v207
	v_fma_f32 v174, v174, v224, v208
	v_fma_f32 v175, v175, v225, v209
	s_add_u32 s28, s14, 0x1800000
	s_addc_u32 s29, s15, 0
	s_add_u32 s30, s22, 0x60000
	s_addc_u32 s31, s23, 0
	v_cvt_pk_bf16_f32 v238, v160, v161
	v_cvt_pk_bf16_f32 v239, v162, v163
	global_store_dwordx2 v247, v[238:239], s[28:29]
	v_cvt_pk_bf16_f32 v240, v164, v165
	v_cvt_pk_bf16_f32 v241, v166, v167
	global_store_dwordx2 v247, v[240:241], s[28:29] offset:512
	s_nop 0
	v_cvt_pk_bf16_f32 v238, v168, v169
	v_cvt_pk_bf16_f32 v239, v170, v171
	global_store_dwordx2 v247, v[238:239], s[28:29] offset:1024
	v_cvt_pk_bf16_f32 v240, v172, v173
	v_cvt_pk_bf16_f32 v241, v174, v175
	global_store_dwordx2 v247, v[240:241], s[28:29] offset:1536
	v_mul_f32_e32 v226, v160, v0
	v_mul_f32_e32 v227, v160, v16
	v_mul_f32_e32 v228, v160, v32
	v_mul_f32_e32 v229, v160, v48
	v_mul_f32_e32 v230, v160, v64
	v_mul_f32_e32 v231, v160, v80
	v_mul_f32_e32 v232, v160, v96
	v_mul_f32_e32 v233, v160, v112
	v_fmac_f32_e32 v226, v161, v1
	v_fmac_f32_e32 v227, v161, v17
	v_fmac_f32_e32 v228, v161, v33
	v_fmac_f32_e32 v229, v161, v49
	v_fmac_f32_e32 v230, v161, v65
	v_fmac_f32_e32 v231, v161, v81
	v_fmac_f32_e32 v232, v161, v97
	v_fmac_f32_e32 v233, v161, v113
	v_fmac_f32_e32 v226, v162, v2
	v_fmac_f32_e32 v227, v162, v18
	v_fmac_f32_e32 v228, v162, v34
	v_fmac_f32_e32 v229, v162, v50
	v_fmac_f32_e32 v230, v162, v66
	v_fmac_f32_e32 v231, v162, v82
	v_fmac_f32_e32 v232, v162, v98
	v_fmac_f32_e32 v233, v162, v114
	v_fmac_f32_e32 v226, v163, v3
	v_fmac_f32_e32 v227, v163, v19
	v_fmac_f32_e32 v228, v163, v35
	v_fmac_f32_e32 v229, v163, v51
	v_fmac_f32_e32 v230, v163, v67
	v_fmac_f32_e32 v231, v163, v83
	v_fmac_f32_e32 v232, v163, v99
	v_fmac_f32_e32 v233, v163, v115
	v_fmac_f32_e32 v226, v164, v4
	v_fmac_f32_e32 v227, v164, v20
	v_fmac_f32_e32 v228, v164, v36
	v_fmac_f32_e32 v229, v164, v52
	v_fmac_f32_e32 v230, v164, v68
	v_fmac_f32_e32 v231, v164, v84
	v_fmac_f32_e32 v232, v164, v100
	v_fmac_f32_e32 v233, v164, v116
	v_fmac_f32_e32 v226, v165, v5
	v_fmac_f32_e32 v227, v165, v21
	v_fmac_f32_e32 v228, v165, v37
	v_fmac_f32_e32 v229, v165, v53
	v_fmac_f32_e32 v230, v165, v69
	v_fmac_f32_e32 v231, v165, v85
	v_fmac_f32_e32 v232, v165, v101
	v_fmac_f32_e32 v233, v165, v117
	v_fmac_f32_e32 v226, v166, v6
	v_fmac_f32_e32 v227, v166, v22
	v_fmac_f32_e32 v228, v166, v38
	v_fmac_f32_e32 v229, v166, v54
	v_fmac_f32_e32 v230, v166, v70
	v_fmac_f32_e32 v231, v166, v86
	v_fmac_f32_e32 v232, v166, v102
	v_fmac_f32_e32 v233, v166, v118
	v_fmac_f32_e32 v226, v167, v7
	v_fmac_f32_e32 v227, v167, v23
	v_fmac_f32_e32 v228, v167, v39
	v_fmac_f32_e32 v229, v167, v55
	v_fmac_f32_e32 v230, v167, v71
	v_fmac_f32_e32 v231, v167, v87
	v_fmac_f32_e32 v232, v167, v103
	v_fmac_f32_e32 v233, v167, v119
	v_fmac_f32_e32 v226, v168, v8
	v_fmac_f32_e32 v227, v168, v24
	v_fmac_f32_e32 v228, v168, v40
	v_fmac_f32_e32 v229, v168, v56
	v_fmac_f32_e32 v230, v168, v72
	v_fmac_f32_e32 v231, v168, v88
	v_fmac_f32_e32 v232, v168, v104
	v_fmac_f32_e32 v233, v168, v120
	v_fmac_f32_e32 v226, v169, v9
	v_fmac_f32_e32 v227, v169, v25
	v_fmac_f32_e32 v228, v169, v41
	v_fmac_f32_e32 v229, v169, v57
	v_fmac_f32_e32 v230, v169, v73
	v_fmac_f32_e32 v231, v169, v89
	v_fmac_f32_e32 v232, v169, v105
	v_fmac_f32_e32 v233, v169, v121
	v_fmac_f32_e32 v226, v170, v10
	v_fmac_f32_e32 v227, v170, v26
	v_fmac_f32_e32 v228, v170, v42
	v_fmac_f32_e32 v229, v170, v58
	v_fmac_f32_e32 v230, v170, v74
	v_fmac_f32_e32 v231, v170, v90
	v_fmac_f32_e32 v232, v170, v106
	v_fmac_f32_e32 v233, v170, v122
	v_fmac_f32_e32 v226, v171, v11
	v_fmac_f32_e32 v227, v171, v27
	v_fmac_f32_e32 v228, v171, v43
	v_fmac_f32_e32 v229, v171, v59
	v_fmac_f32_e32 v230, v171, v75
	v_fmac_f32_e32 v231, v171, v91
	v_fmac_f32_e32 v232, v171, v107
	v_fmac_f32_e32 v233, v171, v123
	v_fmac_f32_e32 v226, v172, v12
	v_fmac_f32_e32 v227, v172, v28
	v_fmac_f32_e32 v228, v172, v44
	v_fmac_f32_e32 v229, v172, v60
	v_fmac_f32_e32 v230, v172, v76
	v_fmac_f32_e32 v231, v172, v92
	v_fmac_f32_e32 v232, v172, v108
	v_fmac_f32_e32 v233, v172, v124
	v_fmac_f32_e32 v226, v173, v13
	v_fmac_f32_e32 v227, v173, v29
	v_fmac_f32_e32 v228, v173, v45
	v_fmac_f32_e32 v229, v173, v61
	v_fmac_f32_e32 v230, v173, v77
	v_fmac_f32_e32 v231, v173, v93
	v_fmac_f32_e32 v232, v173, v109
	v_fmac_f32_e32 v233, v173, v125
	v_fmac_f32_e32 v226, v174, v14
	v_fmac_f32_e32 v227, v174, v30
	v_fmac_f32_e32 v228, v174, v46
	v_fmac_f32_e32 v229, v174, v62
	v_fmac_f32_e32 v230, v174, v78
	v_fmac_f32_e32 v231, v174, v94
	v_fmac_f32_e32 v232, v174, v110
	v_fmac_f32_e32 v233, v174, v126
	v_fmac_f32_e32 v226, v175, v15
	v_fmac_f32_e32 v227, v175, v31
	v_fmac_f32_e32 v228, v175, v47
	v_fmac_f32_e32 v229, v175, v63
	v_fmac_f32_e32 v230, v175, v79
	v_fmac_f32_e32 v231, v175, v95
	v_fmac_f32_e32 v232, v175, v111
	v_fmac_f32_e32 v233, v175, v127
	v_add_f32_dpp v226, v226, v226 quad_perm:[1,0,3,2] row_mask:0xf bank_mask:0xf
	v_add_f32_dpp v227, v227, v227 quad_perm:[1,0,3,2] row_mask:0xf bank_mask:0xf
	v_add_f32_dpp v228, v228, v228 quad_perm:[1,0,3,2] row_mask:0xf bank_mask:0xf
	v_add_f32_dpp v229, v229, v229 quad_perm:[1,0,3,2] row_mask:0xf bank_mask:0xf
	v_add_f32_dpp v230, v230, v230 quad_perm:[1,0,3,2] row_mask:0xf bank_mask:0xf
	v_add_f32_dpp v231, v231, v231 quad_perm:[1,0,3,2] row_mask:0xf bank_mask:0xf
	v_add_f32_dpp v232, v232, v232 quad_perm:[1,0,3,2] row_mask:0xf bank_mask:0xf
	v_add_f32_dpp v233, v233, v233 quad_perm:[1,0,3,2] row_mask:0xf bank_mask:0xf
	v_add_f32_dpp v226, v226, v226 quad_perm:[2,3,0,1] row_mask:0xf bank_mask:0xf
	v_add_f32_dpp v227, v227, v227 quad_perm:[2,3,0,1] row_mask:0xf bank_mask:0xf
	v_add_f32_dpp v228, v228, v228 quad_perm:[2,3,0,1] row_mask:0xf bank_mask:0xf
	v_add_f32_dpp v229, v229, v229 quad_perm:[2,3,0,1] row_mask:0xf bank_mask:0xf
	v_add_f32_dpp v230, v230, v230 quad_perm:[2,3,0,1] row_mask:0xf bank_mask:0xf
	v_add_f32_dpp v231, v231, v231 quad_perm:[2,3,0,1] row_mask:0xf bank_mask:0xf
	v_add_f32_dpp v232, v232, v232 quad_perm:[2,3,0,1] row_mask:0xf bank_mask:0xf
	v_add_f32_dpp v233, v233, v233 quad_perm:[2,3,0,1] row_mask:0xf bank_mask:0xf
	v_add_f32_dpp v226, v226, v226 row_half_mirror row_mask:0xf bank_mask:0xf
	v_add_f32_dpp v227, v227, v227 row_half_mirror row_mask:0xf bank_mask:0xf
	v_add_f32_dpp v228, v228, v228 row_half_mirror row_mask:0xf bank_mask:0xf
	v_add_f32_dpp v229, v229, v229 row_half_mirror row_mask:0xf bank_mask:0xf
	v_add_f32_dpp v230, v230, v230 row_half_mirror row_mask:0xf bank_mask:0xf
	v_add_f32_dpp v231, v231, v231 row_half_mirror row_mask:0xf bank_mask:0xf
	v_add_f32_dpp v232, v232, v232 row_half_mirror row_mask:0xf bank_mask:0xf
	v_add_f32_dpp v233, v233, v233 row_half_mirror row_mask:0xf bank_mask:0xf
	v_add_f32_dpp v226, v226, v226 row_mirror row_mask:0xf bank_mask:0xf
	v_add_f32_dpp v227, v227, v227 row_mirror row_mask:0xf bank_mask:0xf
	v_add_f32_dpp v228, v228, v228 row_mirror row_mask:0xf bank_mask:0xf
	v_add_f32_dpp v229, v229, v229 row_mirror row_mask:0xf bank_mask:0xf
	v_add_f32_dpp v230, v230, v230 row_mirror row_mask:0xf bank_mask:0xf
	v_add_f32_dpp v231, v231, v231 row_mirror row_mask:0xf bank_mask:0xf
	v_add_f32_dpp v232, v232, v232 row_mirror row_mask:0xf bank_mask:0xf
	v_add_f32_dpp v233, v233, v233 row_mirror row_mask:0xf bank_mask:0xf
	v_add_f32_dpp v226, v226, v226 row_bcast:15 row_mask:0xa bank_mask:0xf
	v_add_f32_dpp v227, v227, v227 row_bcast:15 row_mask:0xa bank_mask:0xf
	v_add_f32_dpp v228, v228, v228 row_bcast:15 row_mask:0xa bank_mask:0xf
	v_add_f32_dpp v229, v229, v229 row_bcast:15 row_mask:0xa bank_mask:0xf
	v_add_f32_dpp v230, v230, v230 row_bcast:15 row_mask:0xa bank_mask:0xf
	v_add_f32_dpp v231, v231, v231 row_bcast:15 row_mask:0xa bank_mask:0xf
	v_add_f32_dpp v232, v232, v232 row_bcast:15 row_mask:0xa bank_mask:0xf
	v_add_f32_dpp v233, v233, v233 row_bcast:15 row_mask:0xa bank_mask:0xf
	v_add_f32_dpp v226, v226, v226 row_bcast:31 row_mask:0xc bank_mask:0xf
	v_add_f32_dpp v227, v227, v227 row_bcast:31 row_mask:0xc bank_mask:0xf
	v_add_f32_dpp v228, v228, v228 row_bcast:31 row_mask:0xc bank_mask:0xf
	v_add_f32_dpp v229, v229, v229 row_bcast:31 row_mask:0xc bank_mask:0xf
	v_add_f32_dpp v230, v230, v230 row_bcast:31 row_mask:0xc bank_mask:0xf
	v_add_f32_dpp v231, v231, v231 row_bcast:31 row_mask:0xc bank_mask:0xf
	v_add_f32_dpp v232, v232, v232 row_bcast:31 row_mask:0xc bank_mask:0xf
	v_add_f32_dpp v233, v233, v233 row_bcast:31 row_mask:0xc bank_mask:0xf
	v_readlane_b32 s44, v226, 63
	v_readlane_b32 s45, v227, 63
	v_readlane_b32 s46, v228, 63
	v_readlane_b32 s47, v229, 63
	v_readlane_b32 s48, v230, 63
	v_readlane_b32 s49, v231, 63
	v_readlane_b32 s50, v232, 63
	v_readlane_b32 s51, v233, 63
	s_nop 3
	v_mov_b32_e32 v250, s44
	v_mov_b32_e32 v251, s45
	v_mov_b32_e32 v252, s46
	v_mov_b32_e32 v253, s47
	v_add_f32_e32 v250, s52, v250
	v_add_f32_e32 v251, s53, v251
	v_add_f32_e32 v252, s54, v252
	v_add_f32_e32 v253, s55, v253
	s_mov_b64 exec, 1
	global_store_dwordx4 v246, v[250:253], s[30:31]
	s_nop 1
	v_mov_b32_e32 v250, s48
	v_mov_b32_e32 v251, s49
	v_mov_b32_e32 v252, s50
	v_mov_b32_e32 v253, s51
	v_add_f32_e32 v250, s56, v250
	v_add_f32_e32 v251, s57, v251
	v_add_f32_e32 v252, s58, v252
	v_add_f32_e32 v253, s59, v253
	global_store_dwordx4 v246, v[250:253], s[30:31] offset:16
	s_mov_b64 exec, -1
	s_waitcnt vmcnt(18)
	v_add_f32_e32 v234, v176, v177
	v_mul_f32_e32 v235, v176, v176
	v_add_f32_e32 v238, v178, v179
	v_mul_f32_e32 v239, v177, v177
	v_fmac_f32_e32 v235, v178, v178
	v_fmac_f32_e32 v239, v179, v179
	v_fmac_f32_e32 v235, v180, v180
	v_fmac_f32_e32 v239, v181, v181
	v_add_f32_e32 v234, v234, v180
	v_add_f32_e32 v238, v238, v181
	v_fmac_f32_e32 v235, v182, v182
	v_fmac_f32_e32 v239, v183, v183
	v_add_f32_e32 v234, v234, v182
	v_add_f32_e32 v238, v238, v183
	v_fmac_f32_e32 v235, v184, v184
	v_fmac_f32_e32 v239, v185, v185
	v_add_f32_e32 v234, v234, v184
	v_add_f32_e32 v238, v238, v185
	v_fmac_f32_e32 v235, v186, v186
	v_fmac_f32_e32 v239, v187, v187
	v_add_f32_e32 v234, v234, v186
	v_add_f32_e32 v238, v238, v187
	v_fmac_f32_e32 v235, v188, v188
	v_fmac_f32_e32 v239, v189, v189
	v_add_f32_e32 v234, v234, v188
	v_add_f32_e32 v238, v238, v189
	v_fmac_f32_e32 v235, v190, v190
	v_fmac_f32_e32 v239, v191, v191
	v_add_f32_e32 v234, v234, v190
	v_add_f32_e32 v238, v238, v191
	v_add_f32_e32 v234, v234, v238
	v_add_f32_e32 v235, v235, v239
	s_nop 1
	v_add_f32_dpp v234, v234, v234 quad_perm:[1,0,3,2] row_mask:0xf bank_mask:0xf
	v_add_f32_dpp v235, v235, v235 quad_perm:[1,0,3,2] row_mask:0xf bank_mask:0xf
	s_nop 1
	v_add_f32_dpp v234, v234, v234 quad_perm:[2,3,0,1] row_mask:0xf bank_mask:0xf
	v_add_f32_dpp v235, v235, v235 quad_perm:[2,3,0,1] row_mask:0xf bank_mask:0xf
	s_nop 1
	v_add_f32_dpp v234, v234, v234 row_half_mirror row_mask:0xf bank_mask:0xf
	v_add_f32_dpp v235, v235, v235 row_half_mirror row_mask:0xf bank_mask:0xf
	s_nop 1
	v_add_f32_dpp v234, v234, v234 row_mirror row_mask:0xf bank_mask:0xf
	v_add_f32_dpp v235, v235, v235 row_mirror row_mask:0xf bank_mask:0xf
	s_nop 1
	v_add_f32_dpp v234, v234, v234 row_bcast:15 row_mask:0xa bank_mask:0xf
	v_add_f32_dpp v235, v235, v235 row_bcast:15 row_mask:0xa bank_mask:0xf
	s_nop 1
	v_add_f32_dpp v234, v234, v234 row_bcast:31 row_mask:0xc bank_mask:0xf
	v_add_f32_dpp v235, v235, v235 row_bcast:31 row_mask:0xc bank_mask:0xf
	s_nop 1
	v_readlane_b32 s40, v234, 63
	v_readlane_b32 s41, v235, 63
	s_nop 3
	v_mov_b32_e32 v238, s40
	v_mov_b32_e32 v239, s41
	v_mul_f32_e32 v236, s39, v238
	v_mul_f32_e32 v239, s39, v239
	v_fma_f32 v239, -v236, v236, v239
	v_max_f32_e32 v239, 0x0, v239
	v_add_f32_e32 v239, 0x3727c5ac, v239
	v_rsq_f32_e32 v237, v239
	v_sub_f32_e32 v176, v176, v236
	v_sub_f32_e32 v177, v177, v236
	v_sub_f32_e32 v178, v178, v236
	v_sub_f32_e32 v179, v179, v236
	v_sub_f32_e32 v180, v180, v236
	v_sub_f32_e32 v181, v181, v236
	v_sub_f32_e32 v182, v182, v236
	v_sub_f32_e32 v183, v183, v236
	v_sub_f32_e32 v184, v184, v236
	v_sub_f32_e32 v185, v185, v236
	v_sub_f32_e32 v186, v186, v236
	v_sub_f32_e32 v187, v187, v236
	v_sub_f32_e32 v188, v188, v236
	v_sub_f32_e32 v189, v189, v236
	v_sub_f32_e32 v190, v190, v236
	v_sub_f32_e32 v191, v191, v236
	v_mul_f32_e32 v176, v176, v237
	v_mul_f32_e32 v177, v177, v237
	v_mul_f32_e32 v178, v178, v237
	v_mul_f32_e32 v179, v179, v237
	v_mul_f32_e32 v180, v180, v237
	v_mul_f32_e32 v181, v181, v237
	v_mul_f32_e32 v182, v182, v237
	v_mul_f32_e32 v183, v183, v237
	v_mul_f32_e32 v184, v184, v237
	v_mul_f32_e32 v185, v185, v237
	v_mul_f32_e32 v186, v186, v237
	v_mul_f32_e32 v187, v187, v237
	v_mul_f32_e32 v188, v188, v237
	v_mul_f32_e32 v189, v189, v237
	v_mul_f32_e32 v190, v190, v237
	v_mul_f32_e32 v191, v191, v237
	v_fma_f32 v176, v176, v210, v194
	v_fma_f32 v177, v177, v211, v195
	v_fma_f32 v178, v178, v212, v196
	v_fma_f32 v179, v179, v213, v197
	v_fma_f32 v180, v180, v214, v198
	v_fma_f32 v181, v181, v215, v199
	v_fma_f32 v182, v182, v216, v200
	v_fma_f32 v183, v183, v217, v201
	v_fma_f32 v184, v184, v218, v202
	v_fma_f32 v185, v185, v219, v203
	v_fma_f32 v186, v186, v220, v204
	v_fma_f32 v187, v187, v221, v205
	v_fma_f32 v188, v188, v222, v206
	v_fma_f32 v189, v189, v223, v207
	v_fma_f32 v190, v190, v224, v208
	v_fma_f32 v191, v191, v225, v209
	s_add_u32 s28, s14, 0x1c00000
	s_addc_u32 s29, s15, 0
	s_add_u32 s30, s22, 0x70000
	s_addc_u32 s31, s23, 0
	v_cvt_pk_bf16_f32 v238, v176, v177
	v_cvt_pk_bf16_f32 v239, v178, v179
	global_store_dwordx2 v247, v[238:239], s[28:29]
	v_cvt_pk_bf16_f32 v240, v180, v181
	v_cvt_pk_bf16_f32 v241, v182, v183
	global_store_dwordx2 v247, v[240:241], s[28:29] offset:512
	s_nop 0
	v_cvt_pk_bf16_f32 v238, v184, v185
	v_cvt_pk_bf16_f32 v239, v186, v187
	global_store_dwordx2 v247, v[238:239], s[28:29] offset:1024
	v_cvt_pk_bf16_f32 v240, v188, v189
	v_cvt_pk_bf16_f32 v241, v190, v191
	global_store_dwordx2 v247, v[240:241], s[28:29] offset:1536
	v_mul_f32_e32 v226, v176, v0
	v_mul_f32_e32 v227, v176, v16
	v_mul_f32_e32 v228, v176, v32
	v_mul_f32_e32 v229, v176, v48
	v_mul_f32_e32 v230, v176, v64
	v_mul_f32_e32 v231, v176, v80
	v_mul_f32_e32 v232, v176, v96
	v_mul_f32_e32 v233, v176, v112
	v_fmac_f32_e32 v226, v177, v1
	v_fmac_f32_e32 v227, v177, v17
	v_fmac_f32_e32 v228, v177, v33
	v_fmac_f32_e32 v229, v177, v49
	v_fmac_f32_e32 v230, v177, v65
	v_fmac_f32_e32 v231, v177, v81
	v_fmac_f32_e32 v232, v177, v97
	v_fmac_f32_e32 v233, v177, v113
	v_fmac_f32_e32 v226, v178, v2
	v_fmac_f32_e32 v227, v178, v18
	v_fmac_f32_e32 v228, v178, v34
	v_fmac_f32_e32 v229, v178, v50
	v_fmac_f32_e32 v230, v178, v66
	v_fmac_f32_e32 v231, v178, v82
	v_fmac_f32_e32 v232, v178, v98
	v_fmac_f32_e32 v233, v178, v114
	v_fmac_f32_e32 v226, v179, v3
	v_fmac_f32_e32 v227, v179, v19
	v_fmac_f32_e32 v228, v179, v35
	v_fmac_f32_e32 v229, v179, v51
	v_fmac_f32_e32 v230, v179, v67
	v_fmac_f32_e32 v231, v179, v83
	v_fmac_f32_e32 v232, v179, v99
	v_fmac_f32_e32 v233, v179, v115
	v_fmac_f32_e32 v226, v180, v4
	v_fmac_f32_e32 v227, v180, v20
	v_fmac_f32_e32 v228, v180, v36
	v_fmac_f32_e32 v229, v180, v52
	v_fmac_f32_e32 v230, v180, v68
	v_fmac_f32_e32 v231, v180, v84
	v_fmac_f32_e32 v232, v180, v100
	v_fmac_f32_e32 v233, v180, v116
	v_fmac_f32_e32 v226, v181, v5
	v_fmac_f32_e32 v227, v181, v21
	v_fmac_f32_e32 v228, v181, v37
	v_fmac_f32_e32 v229, v181, v53
	v_fmac_f32_e32 v230, v181, v69
	v_fmac_f32_e32 v231, v181, v85
	v_fmac_f32_e32 v232, v181, v101
	v_fmac_f32_e32 v233, v181, v117
	v_fmac_f32_e32 v226, v182, v6
	v_fmac_f32_e32 v227, v182, v22
	v_fmac_f32_e32 v228, v182, v38
	v_fmac_f32_e32 v229, v182, v54
	v_fmac_f32_e32 v230, v182, v70
	v_fmac_f32_e32 v231, v182, v86
	v_fmac_f32_e32 v232, v182, v102
	v_fmac_f32_e32 v233, v182, v118
	v_fmac_f32_e32 v226, v183, v7
	v_fmac_f32_e32 v227, v183, v23
	v_fmac_f32_e32 v228, v183, v39
	v_fmac_f32_e32 v229, v183, v55
	v_fmac_f32_e32 v230, v183, v71
	v_fmac_f32_e32 v231, v183, v87
	v_fmac_f32_e32 v232, v183, v103
	v_fmac_f32_e32 v233, v183, v119
	v_fmac_f32_e32 v226, v184, v8
	v_fmac_f32_e32 v227, v184, v24
	v_fmac_f32_e32 v228, v184, v40
	v_fmac_f32_e32 v229, v184, v56
	v_fmac_f32_e32 v230, v184, v72
	v_fmac_f32_e32 v231, v184, v88
	v_fmac_f32_e32 v232, v184, v104
	v_fmac_f32_e32 v233, v184, v120
	v_fmac_f32_e32 v226, v185, v9
	v_fmac_f32_e32 v227, v185, v25
	v_fmac_f32_e32 v228, v185, v41
	v_fmac_f32_e32 v229, v185, v57
	v_fmac_f32_e32 v230, v185, v73
	v_fmac_f32_e32 v231, v185, v89
	v_fmac_f32_e32 v232, v185, v105
	v_fmac_f32_e32 v233, v185, v121
	v_fmac_f32_e32 v226, v186, v10
	v_fmac_f32_e32 v227, v186, v26
	v_fmac_f32_e32 v228, v186, v42
	v_fmac_f32_e32 v229, v186, v58
	v_fmac_f32_e32 v230, v186, v74
	v_fmac_f32_e32 v231, v186, v90
	v_fmac_f32_e32 v232, v186, v106
	v_fmac_f32_e32 v233, v186, v122
	v_fmac_f32_e32 v226, v187, v11
	v_fmac_f32_e32 v227, v187, v27
	v_fmac_f32_e32 v228, v187, v43
	v_fmac_f32_e32 v229, v187, v59
	v_fmac_f32_e32 v230, v187, v75
	v_fmac_f32_e32 v231, v187, v91
	v_fmac_f32_e32 v232, v187, v107
	v_fmac_f32_e32 v233, v187, v123
	v_fmac_f32_e32 v226, v188, v12
	v_fmac_f32_e32 v227, v188, v28
	v_fmac_f32_e32 v228, v188, v44
	v_fmac_f32_e32 v229, v188, v60
	v_fmac_f32_e32 v230, v188, v76
	v_fmac_f32_e32 v231, v188, v92
	v_fmac_f32_e32 v232, v188, v108
	v_fmac_f32_e32 v233, v188, v124
	v_fmac_f32_e32 v226, v189, v13
	v_fmac_f32_e32 v227, v189, v29
	v_fmac_f32_e32 v228, v189, v45
	v_fmac_f32_e32 v229, v189, v61
	v_fmac_f32_e32 v230, v189, v77
	v_fmac_f32_e32 v231, v189, v93
	v_fmac_f32_e32 v232, v189, v109
	v_fmac_f32_e32 v233, v189, v125
	v_fmac_f32_e32 v226, v190, v14
	v_fmac_f32_e32 v227, v190, v30
	v_fmac_f32_e32 v228, v190, v46
	v_fmac_f32_e32 v229, v190, v62
	v_fmac_f32_e32 v230, v190, v78
	v_fmac_f32_e32 v231, v190, v94
	v_fmac_f32_e32 v232, v190, v110
	v_fmac_f32_e32 v233, v190, v126
	v_fmac_f32_e32 v226, v191, v15
	v_fmac_f32_e32 v227, v191, v31
	v_fmac_f32_e32 v228, v191, v47
	v_fmac_f32_e32 v229, v191, v63
	v_fmac_f32_e32 v230, v191, v79
	v_fmac_f32_e32 v231, v191, v95
	v_fmac_f32_e32 v232, v191, v111
	v_fmac_f32_e32 v233, v191, v127
	v_add_f32_dpp v226, v226, v226 quad_perm:[1,0,3,2] row_mask:0xf bank_mask:0xf
	v_add_f32_dpp v227, v227, v227 quad_perm:[1,0,3,2] row_mask:0xf bank_mask:0xf
	v_add_f32_dpp v228, v228, v228 quad_perm:[1,0,3,2] row_mask:0xf bank_mask:0xf
	v_add_f32_dpp v229, v229, v229 quad_perm:[1,0,3,2] row_mask:0xf bank_mask:0xf
	v_add_f32_dpp v230, v230, v230 quad_perm:[1,0,3,2] row_mask:0xf bank_mask:0xf
	v_add_f32_dpp v231, v231, v231 quad_perm:[1,0,3,2] row_mask:0xf bank_mask:0xf
	v_add_f32_dpp v232, v232, v232 quad_perm:[1,0,3,2] row_mask:0xf bank_mask:0xf
	v_add_f32_dpp v233, v233, v233 quad_perm:[1,0,3,2] row_mask:0xf bank_mask:0xf
	v_add_f32_dpp v226, v226, v226 quad_perm:[2,3,0,1] row_mask:0xf bank_mask:0xf
	v_add_f32_dpp v227, v227, v227 quad_perm:[2,3,0,1] row_mask:0xf bank_mask:0xf
	v_add_f32_dpp v228, v228, v228 quad_perm:[2,3,0,1] row_mask:0xf bank_mask:0xf
	v_add_f32_dpp v229, v229, v229 quad_perm:[2,3,0,1] row_mask:0xf bank_mask:0xf
	v_add_f32_dpp v230, v230, v230 quad_perm:[2,3,0,1] row_mask:0xf bank_mask:0xf
	v_add_f32_dpp v231, v231, v231 quad_perm:[2,3,0,1] row_mask:0xf bank_mask:0xf
	v_add_f32_dpp v232, v232, v232 quad_perm:[2,3,0,1] row_mask:0xf bank_mask:0xf
	v_add_f32_dpp v233, v233, v233 quad_perm:[2,3,0,1] row_mask:0xf bank_mask:0xf
	v_add_f32_dpp v226, v226, v226 row_half_mirror row_mask:0xf bank_mask:0xf
	v_add_f32_dpp v227, v227, v227 row_half_mirror row_mask:0xf bank_mask:0xf
	v_add_f32_dpp v228, v228, v228 row_half_mirror row_mask:0xf bank_mask:0xf
	v_add_f32_dpp v229, v229, v229 row_half_mirror row_mask:0xf bank_mask:0xf
	v_add_f32_dpp v230, v230, v230 row_half_mirror row_mask:0xf bank_mask:0xf
	v_add_f32_dpp v231, v231, v231 row_half_mirror row_mask:0xf bank_mask:0xf
	v_add_f32_dpp v232, v232, v232 row_half_mirror row_mask:0xf bank_mask:0xf
	v_add_f32_dpp v233, v233, v233 row_half_mirror row_mask:0xf bank_mask:0xf
	v_add_f32_dpp v226, v226, v226 row_mirror row_mask:0xf bank_mask:0xf
	v_add_f32_dpp v227, v227, v227 row_mirror row_mask:0xf bank_mask:0xf
	v_add_f32_dpp v228, v228, v228 row_mirror row_mask:0xf bank_mask:0xf
	v_add_f32_dpp v229, v229, v229 row_mirror row_mask:0xf bank_mask:0xf
	v_add_f32_dpp v230, v230, v230 row_mirror row_mask:0xf bank_mask:0xf
	v_add_f32_dpp v231, v231, v231 row_mirror row_mask:0xf bank_mask:0xf
	v_add_f32_dpp v232, v232, v232 row_mirror row_mask:0xf bank_mask:0xf
	v_add_f32_dpp v233, v233, v233 row_mirror row_mask:0xf bank_mask:0xf
	v_add_f32_dpp v226, v226, v226 row_bcast:15 row_mask:0xa bank_mask:0xf
	v_add_f32_dpp v227, v227, v227 row_bcast:15 row_mask:0xa bank_mask:0xf
	v_add_f32_dpp v228, v228, v228 row_bcast:15 row_mask:0xa bank_mask:0xf
	v_add_f32_dpp v229, v229, v229 row_bcast:15 row_mask:0xa bank_mask:0xf
	v_add_f32_dpp v230, v230, v230 row_bcast:15 row_mask:0xa bank_mask:0xf
	v_add_f32_dpp v231, v231, v231 row_bcast:15 row_mask:0xa bank_mask:0xf
	v_add_f32_dpp v232, v232, v232 row_bcast:15 row_mask:0xa bank_mask:0xf
	v_add_f32_dpp v233, v233, v233 row_bcast:15 row_mask:0xa bank_mask:0xf
	v_add_f32_dpp v226, v226, v226 row_bcast:31 row_mask:0xc bank_mask:0xf
	v_add_f32_dpp v227, v227, v227 row_bcast:31 row_mask:0xc bank_mask:0xf
	v_add_f32_dpp v228, v228, v228 row_bcast:31 row_mask:0xc bank_mask:0xf
	v_add_f32_dpp v229, v229, v229 row_bcast:31 row_mask:0xc bank_mask:0xf
	v_add_f32_dpp v230, v230, v230 row_bcast:31 row_mask:0xc bank_mask:0xf
	v_add_f32_dpp v231, v231, v231 row_bcast:31 row_mask:0xc bank_mask:0xf
	v_add_f32_dpp v232, v232, v232 row_bcast:31 row_mask:0xc bank_mask:0xf
	v_add_f32_dpp v233, v233, v233 row_bcast:31 row_mask:0xc bank_mask:0xf
	v_readlane_b32 s44, v226, 63
	v_readlane_b32 s45, v227, 63
	v_readlane_b32 s46, v228, 63
	v_readlane_b32 s47, v229, 63
	v_readlane_b32 s48, v230, 63
	v_readlane_b32 s49, v231, 63
	v_readlane_b32 s50, v232, 63
	v_readlane_b32 s51, v233, 63
	s_nop 3
	v_mov_b32_e32 v250, s44
	v_mov_b32_e32 v251, s45
	v_mov_b32_e32 v252, s46
	v_mov_b32_e32 v253, s47
	v_add_f32_e32 v250, s52, v250
	v_add_f32_e32 v251, s53, v251
	v_add_f32_e32 v252, s54, v252
	v_add_f32_e32 v253, s55, v253
	s_mov_b64 exec, 1
	global_store_dwordx4 v246, v[250:253], s[30:31]
	s_nop 1
	v_mov_b32_e32 v250, s48
	v_mov_b32_e32 v251, s49
	v_mov_b32_e32 v252, s50
	v_mov_b32_e32 v253, s51
	v_add_f32_e32 v250, s56, v250
	v_add_f32_e32 v251, s57, v251
	v_add_f32_e32 v252, s58, v252
	v_add_f32_e32 v253, s59, v253
	global_store_dwordx4 v246, v[250:253], s[30:31] offset:16
	s_mov_b64 exec, -1
	s_cmp_gt_u32 s24, 511
	s_cbranch_scc1 .Lp1_done
	s_lshr_b32 s38, s24, 2
	s_add_u32 s38, s38, 2
	s_mul_i32 s38, s38, 0x6000
	s_add_u32 s34, s18, s38
	s_addc_u32 s35, s19, 0
	s_add_u32 s36, s34, 0x1000
	s_addc_u32 s37, s35, 0
	global_load_dwordx4 v[194:197], v246, s[34:35]
	global_load_dwordx4 v[198:201], v246, s[34:35] offset:1024
	global_load_dwordx4 v[202:205], v246, s[34:35] offset:2048
	global_load_dwordx4 v[206:209], v246, s[34:35] offset:3072
	global_load_dwordx4 v[210:213], v246, s[36:37]
	global_load_dwordx4 v[214:217], v246, s[36:37] offset:1024
	global_load_dwordx4 v[218:221], v246, s[36:37] offset:2048
	global_load_dwordx4 v[222:225], v246, s[36:37] offset:3072
	s_waitcnt vmcnt(0)
	v_add_f32_e32 v210, 1.0, v210
	v_add_f32_e32 v211, 1.0, v211
	v_add_f32_e32 v212, 1.0, v212
	v_add_f32_e32 v213, 1.0, v213
	v_add_f32_e32 v214, 1.0, v214
	v_add_f32_e32 v215, 1.0, v215
	v_add_f32_e32 v216, 1.0, v216
	v_add_f32_e32 v217, 1.0, v217
	v_add_f32_e32 v218, 1.0, v218
	v_add_f32_e32 v219, 1.0, v219
	v_add_f32_e32 v220, 1.0, v220
	v_add_f32_e32 v221, 1.0, v221
	v_add_f32_e32 v222, 1.0, v222
	v_add_f32_e32 v223, 1.0, v223
	v_add_f32_e32 v224, 1.0, v224
	v_add_f32_e32 v225, 1.0, v225
	v_add_f32_e32 v234, v128, v129
	v_mul_f32_e32 v235, v128, v128
	v_add_f32_e32 v238, v130, v131
	v_mul_f32_e32 v239, v129, v129
	v_fmac_f32_e32 v235, v130, v130
	v_fmac_f32_e32 v239, v131, v131
	v_fmac_f32_e32 v235, v132, v132
	v_fmac_f32_e32 v239, v133, v133
	v_add_f32_e32 v234, v234, v132
	v_add_f32_e32 v238, v238, v133
	v_fmac_f32_e32 v235, v134, v134
	v_fmac_f32_e32 v239, v135, v135
	v_add_f32_e32 v234, v234, v134
	v_add_f32_e32 v238, v238, v135
	v_fmac_f32_e32 v235, v136, v136
	v_fmac_f32_e32 v239, v137, v137
	v_add_f32_e32 v234, v234, v136
	v_add_f32_e32 v238, v238, v137
	v_fmac_f32_e32 v235, v138, v138
	v_fmac_f32_e32 v239, v139, v139
	v_add_f32_e32 v234, v234, v138
	v_add_f32_e32 v238, v238, v139
	v_fmac_f32_e32 v235, v140, v140
	v_fmac_f32_e32 v239, v141, v141
	v_add_f32_e32 v234, v234, v140
	v_add_f32_e32 v238, v238, v141
	v_fmac_f32_e32 v235, v142, v142
	v_fmac_f32_e32 v239, v143, v143
	v_add_f32_e32 v234, v234, v142
	v_add_f32_e32 v238, v238, v143
	v_add_f32_e32 v234, v234, v238
	v_add_f32_e32 v235, v235, v239
	s_nop 1
	v_add_f32_dpp v234, v234, v234 quad_perm:[1,0,3,2] row_mask:0xf bank_mask:0xf
	v_add_f32_dpp v235, v235, v235 quad_perm:[1,0,3,2] row_mask:0xf bank_mask:0xf
	s_nop 1
	v_add_f32_dpp v234, v234, v234 quad_perm:[2,3,0,1] row_mask:0xf bank_mask:0xf
	v_add_f32_dpp v235, v235, v235 quad_perm:[2,3,0,1] row_mask:0xf bank_mask:0xf
	s_nop 1
	v_add_f32_dpp v234, v234, v234 row_half_mirror row_mask:0xf bank_mask:0xf
	v_add_f32_dpp v235, v235, v235 row_half_mirror row_mask:0xf bank_mask:0xf
	s_nop 1
	v_add_f32_dpp v234, v234, v234 row_mirror row_mask:0xf bank_mask:0xf
	v_add_f32_dpp v235, v235, v235 row_mirror row_mask:0xf bank_mask:0xf
	s_nop 1
	v_add_f32_dpp v234, v234, v234 row_bcast:15 row_mask:0xa bank_mask:0xf
	v_add_f32_dpp v235, v235, v235 row_bcast:15 row_mask:0xa bank_mask:0xf
	s_nop 1
	v_add_f32_dpp v234, v234, v234 row_bcast:31 row_mask:0xc bank_mask:0xf
	v_add_f32_dpp v235, v235, v235 row_bcast:31 row_mask:0xc bank_mask:0xf
	s_nop 1
	v_readlane_b32 s40, v234, 63
	v_readlane_b32 s41, v235, 63
	s_nop 3
	v_mov_b32_e32 v238, s40
	v_mov_b32_e32 v239, s41
	v_mul_f32_e32 v236, s39, v238
	v_mul_f32_e32 v239, s39, v239
	v_fma_f32 v239, -v236, v236, v239
	v_max_f32_e32 v239, 0x0, v239
	v_add_f32_e32 v239, 0x3727c5ac, v239
	v_rsq_f32_e32 v237, v239
	v_sub_f32_e32 v128, v128, v236
	v_sub_f32_e32 v129, v129, v236
	v_sub_f32_e32 v130, v130, v236
	v_sub_f32_e32 v131, v131, v236
	v_sub_f32_e32 v132, v132, v236
	v_sub_f32_e32 v133, v133, v236
	v_sub_f32_e32 v134, v134, v236
	v_sub_f32_e32 v135, v135, v236
	v_sub_f32_e32 v136, v136, v236
	v_sub_f32_e32 v137, v137, v236
	v_sub_f32_e32 v138, v138, v236
	v_sub_f32_e32 v139, v139, v236
	v_sub_f32_e32 v140, v140, v236
	v_sub_f32_e32 v141, v141, v236
	v_sub_f32_e32 v142, v142, v236
	v_sub_f32_e32 v143, v143, v236
	v_mul_f32_e32 v128, v128, v237
	v_mul_f32_e32 v129, v129, v237
	v_mul_f32_e32 v130, v130, v237
	v_mul_f32_e32 v131, v131, v237
	v_mul_f32_e32 v132, v132, v237
	v_mul_f32_e32 v133, v133, v237
	v_mul_f32_e32 v134, v134, v237
	v_mul_f32_e32 v135, v135, v237
	v_mul_f32_e32 v136, v136, v237
	v_mul_f32_e32 v137, v137, v237
	v_mul_f32_e32 v138, v138, v237
	v_mul_f32_e32 v139, v139, v237
	v_mul_f32_e32 v140, v140, v237
	v_mul_f32_e32 v141, v141, v237
	v_mul_f32_e32 v142, v142, v237
	v_mul_f32_e32 v143, v143, v237
	v_fma_f32 v128, v128, v210, v194
	v_fma_f32 v129, v129, v211, v195
	v_fma_f32 v130, v130, v212, v196
	v_fma_f32 v131, v131, v213, v197
	v_fma_f32 v132, v132, v214, v198
	v_fma_f32 v133, v133, v215, v199
	v_fma_f32 v134, v134, v216, v200
	v_fma_f32 v135, v135, v217, v201
	v_fma_f32 v136, v136, v218, v202
	v_fma_f32 v137, v137, v219, v203
	v_fma_f32 v138, v138, v220, v204
	v_fma_f32 v139, v139, v221, v205
	v_fma_f32 v140, v140, v222, v206
	v_fma_f32 v141, v141, v223, v207
	v_fma_f32 v142, v142, v224, v208
	v_fma_f32 v143, v143, v225, v209
	s_add_u32 s28, s14, 0x2000000
	s_addc_u32 s29, s15, 0
	s_add_u32 s30, s22, 0x80000
	s_addc_u32 s31, s23, 0
	v_cvt_pk_bf16_f32 v238, v128, v129
	v_cvt_pk_bf16_f32 v239, v130, v131
	global_store_dwordx2 v247, v[238:239], s[28:29]
	v_cvt_pk_bf16_f32 v240, v132, v133
	v_cvt_pk_bf16_f32 v241, v134, v135
	global_store_dwordx2 v247, v[240:241], s[28:29] offset:512
	s_nop 0
	v_cvt_pk_bf16_f32 v238, v136, v137
	v_cvt_pk_bf16_f32 v239, v138, v139
	global_store_dwordx2 v247, v[238:239], s[28:29] offset:1024
	v_cvt_pk_bf16_f32 v240, v140, v141
	v_cvt_pk_bf16_f32 v241, v142, v143
	global_store_dwordx2 v247, v[240:241], s[28:29] offset:1536
	v_mul_f32_e32 v226, v128, v0
	v_mul_f32_e32 v227, v128, v16
	v_mul_f32_e32 v228, v128, v32
	v_mul_f32_e32 v229, v128, v48
	v_mul_f32_e32 v230, v128, v64
	v_mul_f32_e32 v231, v128, v80
	v_mul_f32_e32 v232, v128, v96
	v_mul_f32_e32 v233, v128, v112
	v_fmac_f32_e32 v226, v129, v1
	v_fmac_f32_e32 v227, v129, v17
	v_fmac_f32_e32 v228, v129, v33
	v_fmac_f32_e32 v229, v129, v49
	v_fmac_f32_e32 v230, v129, v65
	v_fmac_f32_e32 v231, v129, v81
	v_fmac_f32_e32 v232, v129, v97
	v_fmac_f32_e32 v233, v129, v113
	v_fmac_f32_e32 v226, v130, v2
	v_fmac_f32_e32 v227, v130, v18
	v_fmac_f32_e32 v228, v130, v34
	v_fmac_f32_e32 v229, v130, v50
	v_fmac_f32_e32 v230, v130, v66
	v_fmac_f32_e32 v231, v130, v82
	v_fmac_f32_e32 v232, v130, v98
	v_fmac_f32_e32 v233, v130, v114
	v_fmac_f32_e32 v226, v131, v3
	v_fmac_f32_e32 v227, v131, v19
	v_fmac_f32_e32 v228, v131, v35
	v_fmac_f32_e32 v229, v131, v51
	v_fmac_f32_e32 v230, v131, v67
	v_fmac_f32_e32 v231, v131, v83
	v_fmac_f32_e32 v232, v131, v99
	v_fmac_f32_e32 v233, v131, v115
	v_fmac_f32_e32 v226, v132, v4
	v_fmac_f32_e32 v227, v132, v20
	v_fmac_f32_e32 v228, v132, v36
	v_fmac_f32_e32 v229, v132, v52
	v_fmac_f32_e32 v230, v132, v68
	v_fmac_f32_e32 v231, v132, v84
	v_fmac_f32_e32 v232, v132, v100
	v_fmac_f32_e32 v233, v132, v116
	v_fmac_f32_e32 v226, v133, v5
	v_fmac_f32_e32 v227, v133, v21
	v_fmac_f32_e32 v228, v133, v37
	v_fmac_f32_e32 v229, v133, v53
	v_fmac_f32_e32 v230, v133, v69
	v_fmac_f32_e32 v231, v133, v85
	v_fmac_f32_e32 v232, v133, v101
	v_fmac_f32_e32 v233, v133, v117
	v_fmac_f32_e32 v226, v134, v6
	v_fmac_f32_e32 v227, v134, v22
	v_fmac_f32_e32 v228, v134, v38
	v_fmac_f32_e32 v229, v134, v54
	v_fmac_f32_e32 v230, v134, v70
	v_fmac_f32_e32 v231, v134, v86
	v_fmac_f32_e32 v232, v134, v102
	v_fmac_f32_e32 v233, v134, v118
	v_fmac_f32_e32 v226, v135, v7
	v_fmac_f32_e32 v227, v135, v23
	v_fmac_f32_e32 v228, v135, v39
	v_fmac_f32_e32 v229, v135, v55
	v_fmac_f32_e32 v230, v135, v71
	v_fmac_f32_e32 v231, v135, v87
	v_fmac_f32_e32 v232, v135, v103
	v_fmac_f32_e32 v233, v135, v119
	v_fmac_f32_e32 v226, v136, v8
	v_fmac_f32_e32 v227, v136, v24
	v_fmac_f32_e32 v228, v136, v40
	v_fmac_f32_e32 v229, v136, v56
	v_fmac_f32_e32 v230, v136, v72
	v_fmac_f32_e32 v231, v136, v88
	v_fmac_f32_e32 v232, v136, v104
	v_fmac_f32_e32 v233, v136, v120
	v_fmac_f32_e32 v226, v137, v9
	v_fmac_f32_e32 v227, v137, v25
	v_fmac_f32_e32 v228, v137, v41
	v_fmac_f32_e32 v229, v137, v57
	v_fmac_f32_e32 v230, v137, v73
	v_fmac_f32_e32 v231, v137, v89
	v_fmac_f32_e32 v232, v137, v105
	v_fmac_f32_e32 v233, v137, v121
	v_fmac_f32_e32 v226, v138, v10
	v_fmac_f32_e32 v227, v138, v26
	v_fmac_f32_e32 v228, v138, v42
	v_fmac_f32_e32 v229, v138, v58
	v_fmac_f32_e32 v230, v138, v74
	v_fmac_f32_e32 v231, v138, v90
	v_fmac_f32_e32 v232, v138, v106
	v_fmac_f32_e32 v233, v138, v122
	v_fmac_f32_e32 v226, v139, v11
	v_fmac_f32_e32 v227, v139, v27
	v_fmac_f32_e32 v228, v139, v43
	v_fmac_f32_e32 v229, v139, v59
	v_fmac_f32_e32 v230, v139, v75
	v_fmac_f32_e32 v231, v139, v91
	v_fmac_f32_e32 v232, v139, v107
	v_fmac_f32_e32 v233, v139, v123
	v_fmac_f32_e32 v226, v140, v12
	v_fmac_f32_e32 v227, v140, v28
	v_fmac_f32_e32 v228, v140, v44
	v_fmac_f32_e32 v229, v140, v60
	v_fmac_f32_e32 v230, v140, v76
	v_fmac_f32_e32 v231, v140, v92
	v_fmac_f32_e32 v232, v140, v108
	v_fmac_f32_e32 v233, v140, v124
	v_fmac_f32_e32 v226, v141, v13
	v_fmac_f32_e32 v227, v141, v29
	v_fmac_f32_e32 v228, v141, v45
	v_fmac_f32_e32 v229, v141, v61
	v_fmac_f32_e32 v230, v141, v77
	v_fmac_f32_e32 v231, v141, v93
	v_fmac_f32_e32 v232, v141, v109
	v_fmac_f32_e32 v233, v141, v125
	v_fmac_f32_e32 v226, v142, v14
	v_fmac_f32_e32 v227, v142, v30
	v_fmac_f32_e32 v228, v142, v46
	v_fmac_f32_e32 v229, v142, v62
	v_fmac_f32_e32 v230, v142, v78
	v_fmac_f32_e32 v231, v142, v94
	v_fmac_f32_e32 v232, v142, v110
	v_fmac_f32_e32 v233, v142, v126
	v_fmac_f32_e32 v226, v143, v15
	v_fmac_f32_e32 v227, v143, v31
	v_fmac_f32_e32 v228, v143, v47
	v_fmac_f32_e32 v229, v143, v63
	v_fmac_f32_e32 v230, v143, v79
	v_fmac_f32_e32 v231, v143, v95
	v_fmac_f32_e32 v232, v143, v111
	v_fmac_f32_e32 v233, v143, v127
	v_add_f32_dpp v226, v226, v226 quad_perm:[1,0,3,2] row_mask:0xf bank_mask:0xf
	v_add_f32_dpp v227, v227, v227 quad_perm:[1,0,3,2] row_mask:0xf bank_mask:0xf
	v_add_f32_dpp v228, v228, v228 quad_perm:[1,0,3,2] row_mask:0xf bank_mask:0xf
	v_add_f32_dpp v229, v229, v229 quad_perm:[1,0,3,2] row_mask:0xf bank_mask:0xf
	v_add_f32_dpp v230, v230, v230 quad_perm:[1,0,3,2] row_mask:0xf bank_mask:0xf
	v_add_f32_dpp v231, v231, v231 quad_perm:[1,0,3,2] row_mask:0xf bank_mask:0xf
	v_add_f32_dpp v232, v232, v232 quad_perm:[1,0,3,2] row_mask:0xf bank_mask:0xf
	v_add_f32_dpp v233, v233, v233 quad_perm:[1,0,3,2] row_mask:0xf bank_mask:0xf
	v_add_f32_dpp v226, v226, v226 quad_perm:[2,3,0,1] row_mask:0xf bank_mask:0xf
	v_add_f32_dpp v227, v227, v227 quad_perm:[2,3,0,1] row_mask:0xf bank_mask:0xf
	v_add_f32_dpp v228, v228, v228 quad_perm:[2,3,0,1] row_mask:0xf bank_mask:0xf
	v_add_f32_dpp v229, v229, v229 quad_perm:[2,3,0,1] row_mask:0xf bank_mask:0xf
	v_add_f32_dpp v230, v230, v230 quad_perm:[2,3,0,1] row_mask:0xf bank_mask:0xf
	v_add_f32_dpp v231, v231, v231 quad_perm:[2,3,0,1] row_mask:0xf bank_mask:0xf
	v_add_f32_dpp v232, v232, v232 quad_perm:[2,3,0,1] row_mask:0xf bank_mask:0xf
	v_add_f32_dpp v233, v233, v233 quad_perm:[2,3,0,1] row_mask:0xf bank_mask:0xf
	v_add_f32_dpp v226, v226, v226 row_half_mirror row_mask:0xf bank_mask:0xf
	v_add_f32_dpp v227, v227, v227 row_half_mirror row_mask:0xf bank_mask:0xf
	v_add_f32_dpp v228, v228, v228 row_half_mirror row_mask:0xf bank_mask:0xf
	v_add_f32_dpp v229, v229, v229 row_half_mirror row_mask:0xf bank_mask:0xf
	v_add_f32_dpp v230, v230, v230 row_half_mirror row_mask:0xf bank_mask:0xf
	v_add_f32_dpp v231, v231, v231 row_half_mirror row_mask:0xf bank_mask:0xf
	v_add_f32_dpp v232, v232, v232 row_half_mirror row_mask:0xf bank_mask:0xf
	v_add_f32_dpp v233, v233, v233 row_half_mirror row_mask:0xf bank_mask:0xf
	v_add_f32_dpp v226, v226, v226 row_mirror row_mask:0xf bank_mask:0xf
	v_add_f32_dpp v227, v227, v227 row_mirror row_mask:0xf bank_mask:0xf
	v_add_f32_dpp v228, v228, v228 row_mirror row_mask:0xf bank_mask:0xf
	v_add_f32_dpp v229, v229, v229 row_mirror row_mask:0xf bank_mask:0xf
	v_add_f32_dpp v230, v230, v230 row_mirror row_mask:0xf bank_mask:0xf
	v_add_f32_dpp v231, v231, v231 row_mirror row_mask:0xf bank_mask:0xf
	v_add_f32_dpp v232, v232, v232 row_mirror row_mask:0xf bank_mask:0xf
	v_add_f32_dpp v233, v233, v233 row_mirror row_mask:0xf bank_mask:0xf
	v_add_f32_dpp v226, v226, v226 row_bcast:15 row_mask:0xa bank_mask:0xf
	v_add_f32_dpp v227, v227, v227 row_bcast:15 row_mask:0xa bank_mask:0xf
	v_add_f32_dpp v228, v228, v228 row_bcast:15 row_mask:0xa bank_mask:0xf
	v_add_f32_dpp v229, v229, v229 row_bcast:15 row_mask:0xa bank_mask:0xf
	v_add_f32_dpp v230, v230, v230 row_bcast:15 row_mask:0xa bank_mask:0xf
	v_add_f32_dpp v231, v231, v231 row_bcast:15 row_mask:0xa bank_mask:0xf
	v_add_f32_dpp v232, v232, v232 row_bcast:15 row_mask:0xa bank_mask:0xf
	v_add_f32_dpp v233, v233, v233 row_bcast:15 row_mask:0xa bank_mask:0xf
	v_add_f32_dpp v226, v226, v226 row_bcast:31 row_mask:0xc bank_mask:0xf
	v_add_f32_dpp v227, v227, v227 row_bcast:31 row_mask:0xc bank_mask:0xf
	v_add_f32_dpp v228, v228, v228 row_bcast:31 row_mask:0xc bank_mask:0xf
	v_add_f32_dpp v229, v229, v229 row_bcast:31 row_mask:0xc bank_mask:0xf
	v_add_f32_dpp v230, v230, v230 row_bcast:31 row_mask:0xc bank_mask:0xf
	v_add_f32_dpp v231, v231, v231 row_bcast:31 row_mask:0xc bank_mask:0xf
	v_add_f32_dpp v232, v232, v232 row_bcast:31 row_mask:0xc bank_mask:0xf
	v_add_f32_dpp v233, v233, v233 row_bcast:31 row_mask:0xc bank_mask:0xf
	v_readlane_b32 s44, v226, 63
	v_readlane_b32 s45, v227, 63
	v_readlane_b32 s46, v228, 63
	v_readlane_b32 s47, v229, 63
	v_readlane_b32 s48, v230, 63
	v_readlane_b32 s49, v231, 63
	v_readlane_b32 s50, v232, 63
	v_readlane_b32 s51, v233, 63
	s_nop 3
	v_mov_b32_e32 v250, s44
	v_mov_b32_e32 v251, s45
	v_mov_b32_e32 v252, s46
	v_mov_b32_e32 v253, s47
	v_add_f32_e32 v250, s52, v250
	v_add_f32_e32 v251, s53, v251
	v_add_f32_e32 v252, s54, v252
	v_add_f32_e32 v253, s55, v253
	s_mov_b64 exec, 1
	global_store_dwordx4 v246, v[250:253], s[30:31]
	s_nop 1
	v_mov_b32_e32 v250, s48
	v_mov_b32_e32 v251, s49
	v_mov_b32_e32 v252, s50
	v_mov_b32_e32 v253, s51
	v_add_f32_e32 v250, s56, v250
	v_add_f32_e32 v251, s57, v251
	v_add_f32_e32 v252, s58, v252
	v_add_f32_e32 v253, s59, v253
	global_store_dwordx4 v246, v[250:253], s[30:31] offset:16
	s_mov_b64 exec, -1
.Lp1_done:
	s_branch .LBB0_127
